# weight conversion moved into idle half-round slots of gate/up and W_in GEMM phases (blocks 128-255), 32 loads in flight per item; U0=13312
# speedup vs baseline: 1.0348x; 1.0348x over previous
.LBB0_5:
	s_or_b64 exec, exec, s[4:5]
	s_lshl_b32 s81, s69, 3
	s_lshl_b32 s88, s76, 3
	s_mov_b32 s101, s81
	s_mov_b32 s98, s88
	s_mov_b32 s100, 0
	s_mov_b32 s99, 0x3400
	s_cmpk_eq_u32 s76, 0x100
	s_cbranch_scc1 .Lconv_entry
	s_mov_b32 s99, 0x14100
.Lconv_entry:
	s_mov_b64 s[4:5], s[0:1]
	v_mov_b32_e32 v2, v214
	s_nop 0
	v_readfirstlane_b32 s3, v2
	s_ashr_i32 s6, s3, 6
	s_add_i32 s3, s6, s101
	s_cmp_ge_i32 s3, s99
	s_cbranch_scc1 .Lconv_ret
	s_load_dwordx2 s[4:5], s[4:5], 0x100
	v_lshlrev_b32_e32 v3, 3, v2
	s_lshl_b32 s6, s6, 14
	v_bfe_u32 v22, v2, 3, 3
	v_and_b32_e32 v6, 56, v3
	v_bfe_u32 v1, v2, 5, 1
	s_add_i32 s7, s6, 0
	v_mul_u32_u24_e32 v4, 0x84, v6
	v_lshlrev_b32_e32 v5, 2, v22
	v_add3_u32 v23, s7, v4, v5
	v_mul_u32_u24_e32 v4, 0x84, v1
	v_lshlrev_b32_e32 v2, 2, v2
	s_waitcnt lgkmcnt(0)
	s_add_u32 s24, s4, 0x100000
	v_mov_b32_e32 v3, 0
	v_or_b32_e32 v5, s6, v4
	v_and_b32_e32 v4, 0x7c, v2
	s_addc_u32 s25, s5, 0
	v_or_b32_e32 v24, 8, v22
	v_or_b32_e32 v25, 16, v22
	v_or_b32_e32 v26, 24, v22
	v_add3_u32 v27, v5, v4, 0
	v_mov_b32_e32 v5, v3
	v_or_b32_e32 v28, 14, v1
	v_or_b32_e32 v29, 12, v1
	v_or_b32_e32 v30, 10, v1
	v_or_b32_e32 v31, 8, v1
	v_or_b32_e32 v32, 6, v1
	v_or_b32_e32 v33, 4, v1
	v_or_b32_e32 v34, 2, v1
	s_mov_b64 s[4:5], 0x8a80000
	s_movk_i32 s26, 0x7fff
	s_mov_b32 s27, 0xffff0000
	s_movk_i32 s28, 0x5800
	s_mov_b64 s[6:7], 0x5e80000
	s_mov_b64 s[38:39], 0x5e00000
	s_mov_b64 s[12:13], 0x5600000
	s_movk_i32 s29, 0x5000
	s_mov_b64 s[14:15], 0x4200000
	s_mov_b64 s[16:17], 0x2c00000
	v_lshlrev_b32_e32 v2, 1, v6
	s_branch .LBB0_11
.LBB0_10:
	s_add_i32 s3, s3, s98
	s_cmp_lt_i32 s3, s99
	s_cbranch_scc0 .Lconv_ret

.LBB0_20:
	v_lshl_add_u64 v[36:37], v[20:21], 0, s[20:21]
	v_lshl_add_u64 v[38:39], v[18:19], 0, s[20:21]
	v_lshl_add_u64 v[40:41], v[16:17], 0, s[20:21]
	v_lshl_add_u64 v[42:43], v[14:15], 0, s[20:21]
	v_lshl_add_u64 v[44:45], v[12:13], 0, s[20:21]
	v_lshl_add_u64 v[46:47], v[10:11], 0, s[20:21]
	v_lshl_add_u64 v[48:49], v[8:9], 0, s[20:21]
	v_lshl_add_u64 v[50:51], v[6:7], 0, s[20:21]
	global_load_dword v52, v[36:37], off nt
	global_load_dword v53, v[38:39], off nt
	global_load_dword v54, v[40:41], off nt
	global_load_dword v55, v[42:43], off nt
	global_load_dword v56, v[44:45], off nt
	global_load_dword v57, v[46:47], off nt
	global_load_dword v58, v[48:49], off nt
	global_load_dword v59, v[50:51], off nt
	s_add_u32 s20, s20, 0x20000
	s_addc_u32 s21, s21, 0
	v_lshl_add_u64 v[36:37], v[20:21], 0, s[20:21]
	v_lshl_add_u64 v[38:39], v[18:19], 0, s[20:21]
	v_lshl_add_u64 v[40:41], v[16:17], 0, s[20:21]
	v_lshl_add_u64 v[42:43], v[14:15], 0, s[20:21]
	v_lshl_add_u64 v[44:45], v[12:13], 0, s[20:21]
	v_lshl_add_u64 v[46:47], v[10:11], 0, s[20:21]
	v_lshl_add_u64 v[48:49], v[8:9], 0, s[20:21]
	v_lshl_add_u64 v[50:51], v[6:7], 0, s[20:21]
	global_load_dword v60, v[36:37], off nt
	global_load_dword v61, v[38:39], off nt
	global_load_dword v62, v[40:41], off nt
	global_load_dword v63, v[42:43], off nt
	global_load_dword v64, v[44:45], off nt
	global_load_dword v65, v[46:47], off nt
	global_load_dword v66, v[48:49], off nt
	global_load_dword v67, v[50:51], off nt
	s_add_u32 s20, s20, 0x20000
	s_addc_u32 s21, s21, 0
	v_lshl_add_u64 v[36:37], v[20:21], 0, s[20:21]
	v_lshl_add_u64 v[38:39], v[18:19], 0, s[20:21]
	v_lshl_add_u64 v[40:41], v[16:17], 0, s[20:21]
	v_lshl_add_u64 v[42:43], v[14:15], 0, s[20:21]
	v_lshl_add_u64 v[44:45], v[12:13], 0, s[20:21]
	v_lshl_add_u64 v[46:47], v[10:11], 0, s[20:21]
	v_lshl_add_u64 v[48:49], v[8:9], 0, s[20:21]
	v_lshl_add_u64 v[50:51], v[6:7], 0, s[20:21]
	global_load_dword v68, v[36:37], off nt
	global_load_dword v69, v[38:39], off nt
	global_load_dword v70, v[40:41], off nt
	global_load_dword v71, v[42:43], off nt
	global_load_dword v72, v[44:45], off nt
	global_load_dword v73, v[46:47], off nt
	global_load_dword v74, v[48:49], off nt
	global_load_dword v75, v[50:51], off nt
	s_add_u32 s20, s20, 0x20000
	s_addc_u32 s21, s21, 0
	v_lshl_add_u64 v[36:37], v[20:21], 0, s[20:21]
	v_lshl_add_u64 v[38:39], v[18:19], 0, s[20:21]
	v_lshl_add_u64 v[40:41], v[16:17], 0, s[20:21]
	v_lshl_add_u64 v[42:43], v[14:15], 0, s[20:21]
	v_lshl_add_u64 v[44:45], v[12:13], 0, s[20:21]
	v_lshl_add_u64 v[46:47], v[10:11], 0, s[20:21]
	v_lshl_add_u64 v[48:49], v[8:9], 0, s[20:21]
	v_lshl_add_u64 v[50:51], v[6:7], 0, s[20:21]
	global_load_dword v76, v[36:37], off nt
	global_load_dword v77, v[38:39], off nt
	global_load_dword v78, v[40:41], off nt
	global_load_dword v79, v[42:43], off nt
	global_load_dword v80, v[44:45], off nt
	global_load_dword v81, v[46:47], off nt
	global_load_dword v82, v[48:49], off nt
	global_load_dword v83, v[50:51], off nt
	s_add_u32 s20, s20, 0x20000
	s_addc_u32 s21, s21, 0
	v_add_u32_e32 v36, 0x400, v35
	s_waitcnt vmcnt(30)
	ds_write2_b32 v35, v52, v53 offset1:66
	s_waitcnt vmcnt(28)
	ds_write2_b32 v35, v54, v55 offset0:132 offset1:198
	s_waitcnt vmcnt(26)
	ds_write2_b32 v36, v56, v57 offset0:8 offset1:74
	s_waitcnt vmcnt(24)
	ds_write2_b32 v36, v58, v59 offset0:140 offset1:206
	v_add_u32_e32 v35, 0x840, v35
	v_add_u32_e32 v36, 0x400, v35
	s_waitcnt vmcnt(22)
	ds_write2_b32 v35, v60, v61 offset1:66
	s_waitcnt vmcnt(20)
	ds_write2_b32 v35, v62, v63 offset0:132 offset1:198
	s_waitcnt vmcnt(18)
	ds_write2_b32 v36, v64, v65 offset0:8 offset1:74
	s_waitcnt vmcnt(16)
	ds_write2_b32 v36, v66, v67 offset0:140 offset1:206
	v_add_u32_e32 v35, 0x840, v35
	v_add_u32_e32 v36, 0x400, v35
	s_waitcnt vmcnt(14)
	ds_write2_b32 v35, v68, v69 offset1:66
	s_waitcnt vmcnt(12)
	ds_write2_b32 v35, v70, v71 offset0:132 offset1:198
	s_waitcnt vmcnt(10)
	ds_write2_b32 v36, v72, v73 offset0:8 offset1:74
	s_waitcnt vmcnt(8)
	ds_write2_b32 v36, v74, v75 offset0:140 offset1:206
	v_add_u32_e32 v35, 0x840, v35
	v_add_u32_e32 v36, 0x400, v35
	s_waitcnt vmcnt(6)
	ds_write2_b32 v35, v76, v77 offset1:66
	s_waitcnt vmcnt(4)
	ds_write2_b32 v35, v78, v79 offset0:132 offset1:198
	s_waitcnt vmcnt(2)
	ds_write2_b32 v36, v80, v81 offset0:8 offset1:74
	s_waitcnt vmcnt(0)
	ds_write2_b32 v36, v82, v83 offset0:140 offset1:206
	v_add_u32_e32 v35, 0x840, v35
	s_waitcnt lgkmcnt(0)
	s_lshl_b32 s20, s22, 5
	ds_read2_b32 v[10:11], v23 offset1:8
	s_and_b32 s33, s20, 0x7e0
	s_lshl_b32 s20, s23, 1
	ds_read2_b32 v[14:15], v23 offset0:33 offset1:41
	s_add_u32 s20, s30, s20
	s_addc_u32 s21, s31, 0
	ds_read2_b32 v[16:17], v23 offset0:66 offset1:74
	v_lshl_add_u64 v[6:7], s[20:21], 0, v[2:3]
	ds_read2_b32 v[18:19], v23 offset0:99 offset1:107
	v_lshl_add_u64 v[12:13], v[6:7], 0, s[4:5]
	s_waitcnt lgkmcnt(3)
	v_bfe_u32 v6, v10, 16, 1
	v_add3_u32 v6, v10, v6, s26
	s_waitcnt lgkmcnt(2)
	v_bfe_u32 v7, v14, 16, 1
	ds_read2_b32 v[20:21], v23 offset0:132 offset1:140
	v_lshrrev_b32_e32 v6, 16, v6
	v_add3_u32 v7, v14, v7, s26
	ds_read2_b32 v[36:37], v23 offset0:165 offset1:173
	v_and_or_b32 v6, v7, s27, v6
	s_waitcnt lgkmcnt(3)
	v_bfe_u32 v7, v16, 16, 1
	v_add3_u32 v7, v16, v7, s26
	s_waitcnt lgkmcnt(2)
	v_bfe_u32 v8, v18, 16, 1
	ds_read2_b32 v[38:39], v23 offset0:198 offset1:206
	v_lshrrev_b32_e32 v7, 16, v7
	v_add3_u32 v8, v18, v8, s26
	ds_read2_b32 v[40:41], v23 offset0:231 offset1:239
	v_and_or_b32 v7, v8, s27, v7
	s_waitcnt lgkmcnt(3)
	v_bfe_u32 v8, v20, 16, 1
	v_add3_u32 v8, v20, v8, s26
	s_waitcnt lgkmcnt(2)
	v_bfe_u32 v9, v36, 16, 1
	v_lshrrev_b32_e32 v8, 16, v8
	v_add3_u32 v9, v36, v9, s26
	v_and_or_b32 v8, v9, s27, v8
	s_waitcnt lgkmcnt(1)
	v_bfe_u32 v9, v38, 16, 1
	v_add3_u32 v9, v38, v9, s26
	s_waitcnt lgkmcnt(0)
	v_bfe_u32 v10, v40, 16, 1
	v_lshrrev_b32_e32 v9, 16, v9
	v_add3_u32 v10, v40, v10, s26
	v_and_or_b32 v9, v10, s27, v9
	v_or_b32_e32 v10, s33, v22
	v_mul_u32_u24_e32 v10, 0x1600, v10
	v_lshlrev_b32_e32 v42, 1, v10
	v_mov_b32_e32 v43, v3
	v_lshl_add_u64 v[42:43], v[12:13], 0, v[42:43]
	global_store_dwordx4 v[42:43], v[6:9], off
	v_bfe_u32 v10, v41, 16, 1
	v_add3_u32 v10, v41, v10, s26
	v_bfe_u32 v6, v11, 16, 1
	v_add3_u32 v6, v11, v6, s26
	v_bfe_u32 v7, v15, 16, 1
	v_lshrrev_b32_e32 v6, 16, v6
	v_add3_u32 v7, v15, v7, s26
	v_and_or_b32 v6, v7, s27, v6
	v_bfe_u32 v7, v17, 16, 1
	v_add3_u32 v7, v17, v7, s26
	v_bfe_u32 v8, v19, 16, 1
	v_lshrrev_b32_e32 v7, 16, v7
	v_add3_u32 v8, v19, v8, s26
	v_and_or_b32 v7, v8, s27, v7
	v_bfe_u32 v8, v21, 16, 1
	v_add3_u32 v8, v21, v8, s26
	v_bfe_u32 v9, v37, 16, 1
	v_lshrrev_b32_e32 v8, 16, v8
	v_add3_u32 v9, v37, v9, s26
	v_and_or_b32 v8, v9, s27, v8
	v_bfe_u32 v9, v39, 16, 1
	v_add3_u32 v9, v39, v9, s26
	v_lshrrev_b32_e32 v9, 16, v9
	v_and_or_b32 v9, v10, s27, v9
	v_or_b32_e32 v10, s33, v24
	v_mul_u32_u24_e32 v10, 0x1600, v10
	v_lshlrev_b32_e32 v10, 1, v10
	v_mov_b32_e32 v11, v3
	ds_read2_b32 v[14:15], v23 offset0:16 offset1:24
	v_lshl_add_u64 v[10:11], v[12:13], 0, v[10:11]
	global_store_dwordx4 v[10:11], v[6:9], off
	ds_read2_b32 v[10:11], v23 offset0:49 offset1:57
	ds_read2_b32 v[16:17], v23 offset0:82 offset1:90
	ds_read2_b32 v[18:19], v23 offset0:115 offset1:123
	s_waitcnt lgkmcnt(3)
	v_bfe_u32 v6, v14, 16, 1
	v_add3_u32 v6, v14, v6, s26
	s_waitcnt lgkmcnt(2)
	v_bfe_u32 v7, v10, 16, 1
	ds_read2_b32 v[20:21], v23 offset0:148 offset1:156
	v_lshrrev_b32_e32 v6, 16, v6
	v_add3_u32 v7, v10, v7, s26
	ds_read2_b32 v[36:37], v23 offset0:181 offset1:189
	v_and_or_b32 v6, v7, s27, v6
	s_waitcnt lgkmcnt(3)
	v_bfe_u32 v7, v16, 16, 1
	v_add3_u32 v7, v16, v7, s26
	s_waitcnt lgkmcnt(2)
	v_bfe_u32 v8, v18, 16, 1
	ds_read2_b32 v[38:39], v23 offset0:214 offset1:222
	v_lshrrev_b32_e32 v7, 16, v7
	v_add3_u32 v8, v18, v8, s26
	ds_read2_b32 v[40:41], v23 offset0:247 offset1:255
	v_and_or_b32 v7, v8, s27, v7
	s_waitcnt lgkmcnt(3)
	v_bfe_u32 v8, v20, 16, 1
	v_add3_u32 v8, v20, v8, s26
	s_waitcnt lgkmcnt(2)
	v_bfe_u32 v9, v36, 16, 1
	v_lshrrev_b32_e32 v8, 16, v8
	v_add3_u32 v9, v36, v9, s26
	v_and_or_b32 v8, v9, s27, v8
	s_waitcnt lgkmcnt(1)
	v_bfe_u32 v9, v38, 16, 1
	v_add3_u32 v9, v38, v9, s26
	s_waitcnt lgkmcnt(0)
	v_bfe_u32 v10, v40, 16, 1
	v_lshrrev_b32_e32 v9, 16, v9
	v_add3_u32 v10, v40, v10, s26
	v_and_or_b32 v9, v10, s27, v9
	v_or_b32_e32 v10, s33, v25
	v_mul_u32_u24_e32 v10, 0x1600, v10
	v_lshlrev_b32_e32 v42, 1, v10
	v_mov_b32_e32 v43, v3
	v_lshl_add_u64 v[42:43], v[12:13], 0, v[42:43]
	global_store_dwordx4 v[42:43], v[6:9], off
	v_bfe_u32 v10, v41, 16, 1
	v_add3_u32 v10, v41, v10, s26
	v_bfe_u32 v6, v15, 16, 1
	v_add3_u32 v6, v15, v6, s26
	v_bfe_u32 v7, v11, 16, 1
	v_lshrrev_b32_e32 v6, 16, v6
	v_add3_u32 v7, v11, v7, s26
	v_and_or_b32 v6, v7, s27, v6
	v_bfe_u32 v7, v17, 16, 1
	v_add3_u32 v7, v17, v7, s26
	v_bfe_u32 v8, v19, 16, 1
	v_lshrrev_b32_e32 v7, 16, v7
	v_add3_u32 v8, v19, v8, s26
	v_and_or_b32 v7, v8, s27, v7
	v_bfe_u32 v8, v21, 16, 1
	v_add3_u32 v8, v21, v8, s26
	v_bfe_u32 v9, v37, 16, 1
	v_lshrrev_b32_e32 v8, 16, v8
	v_add3_u32 v9, v37, v9, s26
	v_and_or_b32 v8, v9, s27, v8
	v_bfe_u32 v9, v39, 16, 1
	v_add3_u32 v9, v39, v9, s26
	v_lshrrev_b32_e32 v9, 16, v9
	v_and_or_b32 v9, v10, s27, v9
	v_or_b32_e32 v10, s33, v26
	v_mul_u32_u24_e32 v10, 0x1600, v10
	v_lshlrev_b32_e32 v10, 1, v10
	v_mov_b32_e32 v11, v3
	v_lshl_add_u64 v[10:11], v[12:13], 0, v[10:11]
	global_store_dwordx4 v[10:11], v[6:9], off
	s_waitcnt lgkmcnt(0)
	s_mov_b64 s[20:21], 0

.LBB0_24:
	v_lshl_add_u64 v[36:37], v[20:21], 0, s[20:21]
	v_lshl_add_u64 v[38:39], v[18:19], 0, s[20:21]
	v_lshl_add_u64 v[40:41], v[16:17], 0, s[20:21]
	v_lshl_add_u64 v[42:43], v[14:15], 0, s[20:21]
	v_lshl_add_u64 v[44:45], v[12:13], 0, s[20:21]
	v_lshl_add_u64 v[46:47], v[10:11], 0, s[20:21]
	v_lshl_add_u64 v[48:49], v[8:9], 0, s[20:21]
	v_lshl_add_u64 v[50:51], v[6:7], 0, s[20:21]
	global_load_dword v52, v[36:37], off nt
	global_load_dword v53, v[38:39], off nt
	global_load_dword v54, v[40:41], off nt
	global_load_dword v55, v[42:43], off nt
	global_load_dword v56, v[44:45], off nt
	global_load_dword v57, v[46:47], off nt
	global_load_dword v58, v[48:49], off nt
	global_load_dword v59, v[50:51], off nt
	s_add_u32 s20, s20, 0x58000
	s_addc_u32 s21, s21, 0
	v_lshl_add_u64 v[36:37], v[20:21], 0, s[20:21]
	v_lshl_add_u64 v[38:39], v[18:19], 0, s[20:21]
	v_lshl_add_u64 v[40:41], v[16:17], 0, s[20:21]
	v_lshl_add_u64 v[42:43], v[14:15], 0, s[20:21]
	v_lshl_add_u64 v[44:45], v[12:13], 0, s[20:21]
	v_lshl_add_u64 v[46:47], v[10:11], 0, s[20:21]
	v_lshl_add_u64 v[48:49], v[8:9], 0, s[20:21]
	v_lshl_add_u64 v[50:51], v[6:7], 0, s[20:21]
	global_load_dword v60, v[36:37], off nt
	global_load_dword v61, v[38:39], off nt
	global_load_dword v62, v[40:41], off nt
	global_load_dword v63, v[42:43], off nt
	global_load_dword v64, v[44:45], off nt
	global_load_dword v65, v[46:47], off nt
	global_load_dword v66, v[48:49], off nt
	global_load_dword v67, v[50:51], off nt
	s_add_u32 s20, s20, 0x58000
	s_addc_u32 s21, s21, 0
	v_lshl_add_u64 v[36:37], v[20:21], 0, s[20:21]
	v_lshl_add_u64 v[38:39], v[18:19], 0, s[20:21]
	v_lshl_add_u64 v[40:41], v[16:17], 0, s[20:21]
	v_lshl_add_u64 v[42:43], v[14:15], 0, s[20:21]
	v_lshl_add_u64 v[44:45], v[12:13], 0, s[20:21]
	v_lshl_add_u64 v[46:47], v[10:11], 0, s[20:21]
	v_lshl_add_u64 v[48:49], v[8:9], 0, s[20:21]
	v_lshl_add_u64 v[50:51], v[6:7], 0, s[20:21]
	global_load_dword v68, v[36:37], off nt
	global_load_dword v69, v[38:39], off nt
	global_load_dword v70, v[40:41], off nt
	global_load_dword v71, v[42:43], off nt
	global_load_dword v72, v[44:45], off nt
	global_load_dword v73, v[46:47], off nt
	global_load_dword v74, v[48:49], off nt
	global_load_dword v75, v[50:51], off nt
	s_add_u32 s20, s20, 0x58000
	s_addc_u32 s21, s21, 0
	v_lshl_add_u64 v[36:37], v[20:21], 0, s[20:21]
	v_lshl_add_u64 v[38:39], v[18:19], 0, s[20:21]
	v_lshl_add_u64 v[40:41], v[16:17], 0, s[20:21]
	v_lshl_add_u64 v[42:43], v[14:15], 0, s[20:21]
	v_lshl_add_u64 v[44:45], v[12:13], 0, s[20:21]
	v_lshl_add_u64 v[46:47], v[10:11], 0, s[20:21]
	v_lshl_add_u64 v[48:49], v[8:9], 0, s[20:21]
	v_lshl_add_u64 v[50:51], v[6:7], 0, s[20:21]
	global_load_dword v76, v[36:37], off nt
	global_load_dword v77, v[38:39], off nt
	global_load_dword v78, v[40:41], off nt
	global_load_dword v79, v[42:43], off nt
	global_load_dword v80, v[44:45], off nt
	global_load_dword v81, v[46:47], off nt
	global_load_dword v82, v[48:49], off nt
	global_load_dword v83, v[50:51], off nt
	s_add_u32 s20, s20, 0x58000
	s_addc_u32 s21, s21, 0
	v_add_u32_e32 v36, 0x400, v35
	s_waitcnt vmcnt(30)
	ds_write2_b32 v35, v52, v53 offset1:66
	s_waitcnt vmcnt(28)
	ds_write2_b32 v35, v54, v55 offset0:132 offset1:198
	s_waitcnt vmcnt(26)
	ds_write2_b32 v36, v56, v57 offset0:8 offset1:74
	s_waitcnt vmcnt(24)
	ds_write2_b32 v36, v58, v59 offset0:140 offset1:206
	v_add_u32_e32 v35, 0x840, v35
	v_add_u32_e32 v36, 0x400, v35
	s_waitcnt vmcnt(22)
	ds_write2_b32 v35, v60, v61 offset1:66
	s_waitcnt vmcnt(20)
	ds_write2_b32 v35, v62, v63 offset0:132 offset1:198
	s_waitcnt vmcnt(18)
	ds_write2_b32 v36, v64, v65 offset0:8 offset1:74
	s_waitcnt vmcnt(16)
	ds_write2_b32 v36, v66, v67 offset0:140 offset1:206
	v_add_u32_e32 v35, 0x840, v35
	v_add_u32_e32 v36, 0x400, v35
	s_waitcnt vmcnt(14)
	ds_write2_b32 v35, v68, v69 offset1:66
	s_waitcnt vmcnt(12)
	ds_write2_b32 v35, v70, v71 offset0:132 offset1:198
	s_waitcnt vmcnt(10)
	ds_write2_b32 v36, v72, v73 offset0:8 offset1:74
	s_waitcnt vmcnt(8)
	ds_write2_b32 v36, v74, v75 offset0:140 offset1:206
	v_add_u32_e32 v35, 0x840, v35
	v_add_u32_e32 v36, 0x400, v35
	s_waitcnt vmcnt(6)
	ds_write2_b32 v35, v76, v77 offset1:66
	s_waitcnt vmcnt(4)
	ds_write2_b32 v35, v78, v79 offset0:132 offset1:198
	s_waitcnt vmcnt(2)
	ds_write2_b32 v36, v80, v81 offset0:8 offset1:74
	s_waitcnt vmcnt(0)
	ds_write2_b32 v36, v82, v83 offset0:140 offset1:206
	v_add_u32_e32 v35, 0x840, v35
	s_lshl_b32 s20, s33, 5
	s_lshl_b32 s21, s33, 6
	s_and_b32 s21, s21, 0x3f00
	s_and_b32 s20, s20, 0x60
	s_waitcnt lgkmcnt(0)
	s_or_b32 s20, s21, s20
	s_or_b32 s33, s20, 0x80
	s_and_b32 s20, 0xffff, s23
	ds_read2_b32 v[10:11], v23 offset1:8
	s_lshl_b32 s20, s20, 1
	ds_read2_b32 v[14:15], v23 offset0:33 offset1:41
	s_add_u32 s20, s30, s20
	s_addc_u32 s21, s31, 0
	ds_read2_b32 v[16:17], v23 offset0:66 offset1:74
	v_lshl_add_u64 v[6:7], s[20:21], 0, v[2:3]
	ds_read2_b32 v[18:19], v23 offset0:99 offset1:107
	v_lshl_add_u64 v[12:13], v[6:7], 0, s[6:7]
	s_waitcnt lgkmcnt(3)
	v_bfe_u32 v6, v10, 16, 1
	v_add3_u32 v6, v10, v6, s26
	s_waitcnt lgkmcnt(2)
	v_bfe_u32 v7, v14, 16, 1
	ds_read2_b32 v[20:21], v23 offset0:132 offset1:140
	v_lshrrev_b32_e32 v6, 16, v6
	v_add3_u32 v7, v14, v7, s26
	ds_read2_b32 v[36:37], v23 offset0:165 offset1:173
	v_and_or_b32 v6, v7, s27, v6
	s_waitcnt lgkmcnt(3)
	v_bfe_u32 v7, v16, 16, 1
	v_add3_u32 v7, v16, v7, s26
	s_waitcnt lgkmcnt(2)
	v_bfe_u32 v8, v18, 16, 1
	ds_read2_b32 v[38:39], v23 offset0:198 offset1:206
	v_lshrrev_b32_e32 v7, 16, v7
	v_add3_u32 v8, v18, v8, s26
	ds_read2_b32 v[40:41], v23 offset0:231 offset1:239
	v_and_or_b32 v7, v8, s27, v7
	s_waitcnt lgkmcnt(3)
	v_bfe_u32 v8, v20, 16, 1
	v_add3_u32 v8, v20, v8, s26
	s_waitcnt lgkmcnt(2)
	v_bfe_u32 v9, v36, 16, 1
	v_lshrrev_b32_e32 v8, 16, v8
	v_add3_u32 v9, v36, v9, s26
	v_and_or_b32 v8, v9, s27, v8
	s_waitcnt lgkmcnt(1)
	v_bfe_u32 v9, v38, 16, 1
	v_add3_u32 v9, v38, v9, s26
	s_waitcnt lgkmcnt(0)
	v_bfe_u32 v10, v40, 16, 1
	v_lshrrev_b32_e32 v9, 16, v9
	v_add3_u32 v10, v40, v10, s26
	v_and_or_b32 v9, v10, s27, v9
	v_or_b32_e32 v10, s33, v22
	v_lshlrev_b32_e32 v42, 12, v10
	v_mov_b32_e32 v43, v3
	v_lshl_add_u64 v[42:43], v[12:13], 0, v[42:43]
	global_store_dwordx4 v[42:43], v[6:9], off
	v_bfe_u32 v10, v41, 16, 1
	v_add3_u32 v10, v41, v10, s26
	v_bfe_u32 v6, v11, 16, 1
	v_add3_u32 v6, v11, v6, s26
	v_bfe_u32 v7, v15, 16, 1
	v_lshrrev_b32_e32 v6, 16, v6
	v_add3_u32 v7, v15, v7, s26
	v_and_or_b32 v6, v7, s27, v6
	v_bfe_u32 v7, v17, 16, 1
	v_add3_u32 v7, v17, v7, s26
	v_bfe_u32 v8, v19, 16, 1
	v_lshrrev_b32_e32 v7, 16, v7
	v_add3_u32 v8, v19, v8, s26
	v_and_or_b32 v7, v8, s27, v7
	v_bfe_u32 v8, v21, 16, 1
	v_add3_u32 v8, v21, v8, s26
	v_bfe_u32 v9, v37, 16, 1
	v_lshrrev_b32_e32 v8, 16, v8
	v_add3_u32 v9, v37, v9, s26
	v_and_or_b32 v8, v9, s27, v8
	v_bfe_u32 v9, v39, 16, 1
	v_add3_u32 v9, v39, v9, s26
	v_lshrrev_b32_e32 v9, 16, v9
	v_and_or_b32 v9, v10, s27, v9
	v_or_b32_e32 v10, s33, v24
	v_lshlrev_b32_e32 v10, 12, v10
	v_mov_b32_e32 v11, v3
	ds_read2_b32 v[14:15], v23 offset0:16 offset1:24
	v_lshl_add_u64 v[10:11], v[12:13], 0, v[10:11]
	global_store_dwordx4 v[10:11], v[6:9], off
	ds_read2_b32 v[10:11], v23 offset0:49 offset1:57
	ds_read2_b32 v[16:17], v23 offset0:82 offset1:90
	ds_read2_b32 v[18:19], v23 offset0:115 offset1:123
	s_waitcnt lgkmcnt(3)
	v_bfe_u32 v6, v14, 16, 1
	v_add3_u32 v6, v14, v6, s26
	s_waitcnt lgkmcnt(2)
	v_bfe_u32 v7, v10, 16, 1
	ds_read2_b32 v[20:21], v23 offset0:148 offset1:156
	v_lshrrev_b32_e32 v6, 16, v6
	v_add3_u32 v7, v10, v7, s26
	ds_read2_b32 v[36:37], v23 offset0:181 offset1:189
	v_and_or_b32 v6, v7, s27, v6
	s_waitcnt lgkmcnt(3)
	v_bfe_u32 v7, v16, 16, 1
	v_add3_u32 v7, v16, v7, s26
	s_waitcnt lgkmcnt(2)
	v_bfe_u32 v8, v18, 16, 1
	ds_read2_b32 v[38:39], v23 offset0:214 offset1:222
	v_lshrrev_b32_e32 v7, 16, v7
	v_add3_u32 v8, v18, v8, s26
	ds_read2_b32 v[40:41], v23 offset0:247 offset1:255
	v_and_or_b32 v7, v8, s27, v7
	s_waitcnt lgkmcnt(3)
	v_bfe_u32 v8, v20, 16, 1
	v_add3_u32 v8, v20, v8, s26
	s_waitcnt lgkmcnt(2)
	v_bfe_u32 v9, v36, 16, 1
	v_lshrrev_b32_e32 v8, 16, v8
	v_add3_u32 v9, v36, v9, s26
	v_and_or_b32 v8, v9, s27, v8
	s_waitcnt lgkmcnt(1)
	v_bfe_u32 v9, v38, 16, 1
	v_add3_u32 v9, v38, v9, s26
	s_waitcnt lgkmcnt(0)
	v_bfe_u32 v10, v40, 16, 1
	v_lshrrev_b32_e32 v9, 16, v9
	v_add3_u32 v10, v40, v10, s26
	v_and_or_b32 v9, v10, s27, v9
	v_or_b32_e32 v10, s33, v25
	v_lshlrev_b32_e32 v42, 12, v10
	v_mov_b32_e32 v43, v3
	v_lshl_add_u64 v[42:43], v[12:13], 0, v[42:43]
	global_store_dwordx4 v[42:43], v[6:9], off
	v_bfe_u32 v10, v41, 16, 1
	v_add3_u32 v10, v41, v10, s26
	v_bfe_u32 v6, v15, 16, 1
	v_add3_u32 v6, v15, v6, s26
	v_bfe_u32 v7, v11, 16, 1
	v_lshrrev_b32_e32 v6, 16, v6
	v_add3_u32 v7, v11, v7, s26
	v_and_or_b32 v6, v7, s27, v6
	v_bfe_u32 v7, v17, 16, 1
	v_add3_u32 v7, v17, v7, s26
	v_bfe_u32 v8, v19, 16, 1
	v_lshrrev_b32_e32 v7, 16, v7
	v_add3_u32 v8, v19, v8, s26
	v_and_or_b32 v7, v8, s27, v7
	v_bfe_u32 v8, v21, 16, 1
	v_add3_u32 v8, v21, v8, s26
	v_bfe_u32 v9, v37, 16, 1
	v_lshrrev_b32_e32 v8, 16, v8
	v_add3_u32 v9, v37, v9, s26
	v_and_or_b32 v8, v9, s27, v8
	v_bfe_u32 v9, v39, 16, 1
	v_add3_u32 v9, v39, v9, s26
	v_lshrrev_b32_e32 v9, 16, v9
	v_and_or_b32 v9, v10, s27, v9
	v_or_b32_e32 v10, s33, v26
	v_lshlrev_b32_e32 v10, 12, v10
	v_mov_b32_e32 v11, v3
	v_lshl_add_u64 v[10:11], v[12:13], 0, v[10:11]
	global_store_dwordx4 v[10:11], v[6:9], off
	s_waitcnt lgkmcnt(0)

.LBB0_29:
	v_lshl_add_u64 v[36:37], v[20:21], 0, s[20:21]
	v_lshl_add_u64 v[38:39], v[18:19], 0, s[20:21]
	v_lshl_add_u64 v[40:41], v[16:17], 0, s[20:21]
	v_lshl_add_u64 v[42:43], v[14:15], 0, s[20:21]
	v_lshl_add_u64 v[44:45], v[12:13], 0, s[20:21]
	v_lshl_add_u64 v[46:47], v[10:11], 0, s[20:21]
	v_lshl_add_u64 v[48:49], v[8:9], 0, s[20:21]
	v_lshl_add_u64 v[50:51], v[6:7], 0, s[20:21]
	global_load_dword v52, v[36:37], off nt
	global_load_dword v53, v[38:39], off nt
	global_load_dword v54, v[40:41], off nt
	global_load_dword v55, v[42:43], off nt
	global_load_dword v56, v[44:45], off nt
	global_load_dword v57, v[46:47], off nt
	global_load_dword v58, v[48:49], off nt
	global_load_dword v59, v[50:51], off nt
	s_add_u32 s20, s20, 0x58000
	s_addc_u32 s21, s21, 0
	v_lshl_add_u64 v[36:37], v[20:21], 0, s[20:21]
	v_lshl_add_u64 v[38:39], v[18:19], 0, s[20:21]
	v_lshl_add_u64 v[40:41], v[16:17], 0, s[20:21]
	v_lshl_add_u64 v[42:43], v[14:15], 0, s[20:21]
	v_lshl_add_u64 v[44:45], v[12:13], 0, s[20:21]
	v_lshl_add_u64 v[46:47], v[10:11], 0, s[20:21]
	v_lshl_add_u64 v[48:49], v[8:9], 0, s[20:21]
	v_lshl_add_u64 v[50:51], v[6:7], 0, s[20:21]
	global_load_dword v60, v[36:37], off nt
	global_load_dword v61, v[38:39], off nt
	global_load_dword v62, v[40:41], off nt
	global_load_dword v63, v[42:43], off nt
	global_load_dword v64, v[44:45], off nt
	global_load_dword v65, v[46:47], off nt
	global_load_dword v66, v[48:49], off nt
	global_load_dword v67, v[50:51], off nt
	s_add_u32 s20, s20, 0x58000
	s_addc_u32 s21, s21, 0
	v_lshl_add_u64 v[36:37], v[20:21], 0, s[20:21]
	v_lshl_add_u64 v[38:39], v[18:19], 0, s[20:21]
	v_lshl_add_u64 v[40:41], v[16:17], 0, s[20:21]
	v_lshl_add_u64 v[42:43], v[14:15], 0, s[20:21]
	v_lshl_add_u64 v[44:45], v[12:13], 0, s[20:21]
	v_lshl_add_u64 v[46:47], v[10:11], 0, s[20:21]
	v_lshl_add_u64 v[48:49], v[8:9], 0, s[20:21]
	v_lshl_add_u64 v[50:51], v[6:7], 0, s[20:21]
	global_load_dword v68, v[36:37], off nt
	global_load_dword v69, v[38:39], off nt
	global_load_dword v70, v[40:41], off nt
	global_load_dword v71, v[42:43], off nt
	global_load_dword v72, v[44:45], off nt
	global_load_dword v73, v[46:47], off nt
	global_load_dword v74, v[48:49], off nt
	global_load_dword v75, v[50:51], off nt
	s_add_u32 s20, s20, 0x58000
	s_addc_u32 s21, s21, 0
	v_lshl_add_u64 v[36:37], v[20:21], 0, s[20:21]
	v_lshl_add_u64 v[38:39], v[18:19], 0, s[20:21]
	v_lshl_add_u64 v[40:41], v[16:17], 0, s[20:21]
	v_lshl_add_u64 v[42:43], v[14:15], 0, s[20:21]
	v_lshl_add_u64 v[44:45], v[12:13], 0, s[20:21]
	v_lshl_add_u64 v[46:47], v[10:11], 0, s[20:21]
	v_lshl_add_u64 v[48:49], v[8:9], 0, s[20:21]
	v_lshl_add_u64 v[50:51], v[6:7], 0, s[20:21]
	global_load_dword v76, v[36:37], off nt
	global_load_dword v77, v[38:39], off nt
	global_load_dword v78, v[40:41], off nt
	global_load_dword v79, v[42:43], off nt
	global_load_dword v80, v[44:45], off nt
	global_load_dword v81, v[46:47], off nt
	global_load_dword v82, v[48:49], off nt
	global_load_dword v83, v[50:51], off nt
	s_add_u32 s20, s20, 0x58000
	s_addc_u32 s21, s21, 0
	v_add_u32_e32 v36, 0x400, v35
	s_waitcnt vmcnt(30)
	ds_write2_b32 v35, v52, v53 offset1:66
	s_waitcnt vmcnt(28)
	ds_write2_b32 v35, v54, v55 offset0:132 offset1:198
	s_waitcnt vmcnt(26)
	ds_write2_b32 v36, v56, v57 offset0:8 offset1:74
	s_waitcnt vmcnt(24)
	ds_write2_b32 v36, v58, v59 offset0:140 offset1:206
	v_add_u32_e32 v35, 0x840, v35
	v_add_u32_e32 v36, 0x400, v35
	s_waitcnt vmcnt(22)
	ds_write2_b32 v35, v60, v61 offset1:66
	s_waitcnt vmcnt(20)
	ds_write2_b32 v35, v62, v63 offset0:132 offset1:198
	s_waitcnt vmcnt(18)
	ds_write2_b32 v36, v64, v65 offset0:8 offset1:74
	s_waitcnt vmcnt(16)
	ds_write2_b32 v36, v66, v67 offset0:140 offset1:206
	v_add_u32_e32 v35, 0x840, v35
	v_add_u32_e32 v36, 0x400, v35
	s_waitcnt vmcnt(14)
	ds_write2_b32 v35, v68, v69 offset1:66
	s_waitcnt vmcnt(12)
	ds_write2_b32 v35, v70, v71 offset0:132 offset1:198
	s_waitcnt vmcnt(10)
	ds_write2_b32 v36, v72, v73 offset0:8 offset1:74
	s_waitcnt vmcnt(8)
	ds_write2_b32 v36, v74, v75 offset0:140 offset1:206
	v_add_u32_e32 v35, 0x840, v35
	v_add_u32_e32 v36, 0x400, v35
	s_waitcnt vmcnt(6)
	ds_write2_b32 v35, v76, v77 offset1:66
	s_waitcnt vmcnt(4)
	ds_write2_b32 v35, v78, v79 offset0:132 offset1:198
	s_waitcnt vmcnt(2)
	ds_write2_b32 v36, v80, v81 offset0:8 offset1:74
	s_waitcnt vmcnt(0)
	ds_write2_b32 v36, v82, v83 offset0:140 offset1:206
	v_add_u32_e32 v35, 0x840, v35
	s_lshl_b32 s20, s33, 5
	s_lshl_b32 s21, s33, 6
	s_waitcnt lgkmcnt(0)
	s_and_b32 s21, s21, 0x3f00
	s_and_b32 s20, s20, 0x60
	s_or_b32 s33, s20, s21
	s_and_b32 s20, 0xffff, s23
	ds_read2_b32 v[10:11], v23 offset1:8
	s_lshl_b32 s20, s20, 1
	ds_read2_b32 v[14:15], v23 offset0:33 offset1:41
	s_add_u32 s20, s30, s20
	s_addc_u32 s21, s31, 0
	ds_read2_b32 v[16:17], v23 offset0:66 offset1:74
	v_lshl_add_u64 v[6:7], s[20:21], 0, v[2:3]
	ds_read2_b32 v[18:19], v23 offset0:99 offset1:107
	v_lshl_add_u64 v[12:13], v[6:7], 0, s[6:7]
	s_waitcnt lgkmcnt(3)
	v_bfe_u32 v6, v10, 16, 1
	v_add3_u32 v6, v10, v6, s26
	s_waitcnt lgkmcnt(2)
	v_bfe_u32 v7, v14, 16, 1
	ds_read2_b32 v[20:21], v23 offset0:132 offset1:140
	v_lshrrev_b32_e32 v6, 16, v6
	v_add3_u32 v7, v14, v7, s26
	ds_read2_b32 v[36:37], v23 offset0:165 offset1:173
	v_and_or_b32 v6, v7, s27, v6
	s_waitcnt lgkmcnt(3)
	v_bfe_u32 v7, v16, 16, 1
	v_add3_u32 v7, v16, v7, s26
	s_waitcnt lgkmcnt(2)
	v_bfe_u32 v8, v18, 16, 1
	ds_read2_b32 v[38:39], v23 offset0:198 offset1:206
	v_lshrrev_b32_e32 v7, 16, v7
	v_add3_u32 v8, v18, v8, s26
	ds_read2_b32 v[40:41], v23 offset0:231 offset1:239
	v_and_or_b32 v7, v8, s27, v7
	s_waitcnt lgkmcnt(3)
	v_bfe_u32 v8, v20, 16, 1
	v_add3_u32 v8, v20, v8, s26
	s_waitcnt lgkmcnt(2)
	v_bfe_u32 v9, v36, 16, 1
	v_lshrrev_b32_e32 v8, 16, v8
	v_add3_u32 v9, v36, v9, s26
	v_and_or_b32 v8, v9, s27, v8
	s_waitcnt lgkmcnt(1)
	v_bfe_u32 v9, v38, 16, 1
	v_add3_u32 v9, v38, v9, s26
	s_waitcnt lgkmcnt(0)
	v_bfe_u32 v10, v40, 16, 1
	v_lshrrev_b32_e32 v9, 16, v9
	v_add3_u32 v10, v40, v10, s26
	v_and_or_b32 v9, v10, s27, v9
	v_or_b32_e32 v10, s33, v22
	v_lshlrev_b32_e32 v42, 12, v10
	v_mov_b32_e32 v43, v3
	v_lshl_add_u64 v[42:43], v[12:13], 0, v[42:43]
	global_store_dwordx4 v[42:43], v[6:9], off
	v_bfe_u32 v10, v41, 16, 1
	v_add3_u32 v10, v41, v10, s26
	v_bfe_u32 v6, v11, 16, 1
	v_add3_u32 v6, v11, v6, s26
	v_bfe_u32 v7, v15, 16, 1
	v_lshrrev_b32_e32 v6, 16, v6
	v_add3_u32 v7, v15, v7, s26
	v_and_or_b32 v6, v7, s27, v6
	v_bfe_u32 v7, v17, 16, 1
	v_add3_u32 v7, v17, v7, s26
	v_bfe_u32 v8, v19, 16, 1
	v_lshrrev_b32_e32 v7, 16, v7
	v_add3_u32 v8, v19, v8, s26
	v_and_or_b32 v7, v8, s27, v7
	v_bfe_u32 v8, v21, 16, 1
	v_add3_u32 v8, v21, v8, s26
	v_bfe_u32 v9, v37, 16, 1
	v_lshrrev_b32_e32 v8, 16, v8
	v_add3_u32 v9, v37, v9, s26
	v_and_or_b32 v8, v9, s27, v8
	v_bfe_u32 v9, v39, 16, 1
	v_add3_u32 v9, v39, v9, s26
	v_lshrrev_b32_e32 v9, 16, v9
	v_and_or_b32 v9, v10, s27, v9
	v_or_b32_e32 v10, s33, v24
	v_lshlrev_b32_e32 v10, 12, v10
	v_mov_b32_e32 v11, v3
	ds_read2_b32 v[14:15], v23 offset0:16 offset1:24
	v_lshl_add_u64 v[10:11], v[12:13], 0, v[10:11]
	global_store_dwordx4 v[10:11], v[6:9], off
	ds_read2_b32 v[10:11], v23 offset0:49 offset1:57
	ds_read2_b32 v[16:17], v23 offset0:82 offset1:90
	ds_read2_b32 v[18:19], v23 offset0:115 offset1:123
	s_waitcnt lgkmcnt(3)
	v_bfe_u32 v6, v14, 16, 1
	v_add3_u32 v6, v14, v6, s26
	s_waitcnt lgkmcnt(2)
	v_bfe_u32 v7, v10, 16, 1
	ds_read2_b32 v[20:21], v23 offset0:148 offset1:156
	v_lshrrev_b32_e32 v6, 16, v6
	v_add3_u32 v7, v10, v7, s26
	ds_read2_b32 v[36:37], v23 offset0:181 offset1:189
	v_and_or_b32 v6, v7, s27, v6
	s_waitcnt lgkmcnt(3)
	v_bfe_u32 v7, v16, 16, 1
	v_add3_u32 v7, v16, v7, s26
	s_waitcnt lgkmcnt(2)
	v_bfe_u32 v8, v18, 16, 1
	ds_read2_b32 v[38:39], v23 offset0:214 offset1:222
	v_lshrrev_b32_e32 v7, 16, v7
	v_add3_u32 v8, v18, v8, s26
	ds_read2_b32 v[40:41], v23 offset0:247 offset1:255
	v_and_or_b32 v7, v8, s27, v7
	s_waitcnt lgkmcnt(3)
	v_bfe_u32 v8, v20, 16, 1
	v_add3_u32 v8, v20, v8, s26
	s_waitcnt lgkmcnt(2)
	v_bfe_u32 v9, v36, 16, 1
	v_lshrrev_b32_e32 v8, 16, v8
	v_add3_u32 v9, v36, v9, s26
	v_and_or_b32 v8, v9, s27, v8
	s_waitcnt lgkmcnt(1)
	v_bfe_u32 v9, v38, 16, 1
	v_add3_u32 v9, v38, v9, s26
	s_waitcnt lgkmcnt(0)
	v_bfe_u32 v10, v40, 16, 1
	v_lshrrev_b32_e32 v9, 16, v9
	v_add3_u32 v10, v40, v10, s26
	v_and_or_b32 v9, v10, s27, v9
	v_or_b32_e32 v10, s33, v25
	v_lshlrev_b32_e32 v42, 12, v10
	v_mov_b32_e32 v43, v3
	v_lshl_add_u64 v[42:43], v[12:13], 0, v[42:43]
	global_store_dwordx4 v[42:43], v[6:9], off
	v_bfe_u32 v10, v41, 16, 1
	v_add3_u32 v10, v41, v10, s26
	v_bfe_u32 v6, v15, 16, 1
	v_add3_u32 v6, v15, v6, s26
	v_bfe_u32 v7, v11, 16, 1
	v_lshrrev_b32_e32 v6, 16, v6
	v_add3_u32 v7, v11, v7, s26
	v_and_or_b32 v6, v7, s27, v6
	v_bfe_u32 v7, v17, 16, 1
	v_add3_u32 v7, v17, v7, s26
	v_bfe_u32 v8, v19, 16, 1
	v_lshrrev_b32_e32 v7, 16, v7
	v_add3_u32 v8, v19, v8, s26
	v_and_or_b32 v7, v8, s27, v7
	v_bfe_u32 v8, v21, 16, 1
	v_add3_u32 v8, v21, v8, s26
	v_bfe_u32 v9, v37, 16, 1
	v_lshrrev_b32_e32 v8, 16, v8
	v_add3_u32 v9, v37, v9, s26
	v_and_or_b32 v8, v9, s27, v8
	v_bfe_u32 v9, v39, 16, 1
	v_add3_u32 v9, v39, v9, s26
	v_lshrrev_b32_e32 v9, 16, v9
	v_and_or_b32 v9, v10, s27, v9
	v_or_b32_e32 v10, s33, v26
	v_lshlrev_b32_e32 v10, 12, v10
	v_mov_b32_e32 v11, v3
	v_lshl_add_u64 v[10:11], v[12:13], 0, v[10:11]
	global_store_dwordx4 v[10:11], v[6:9], off
	s_waitcnt lgkmcnt(0)

.LBB0_34:
	v_lshl_add_u64 v[36:37], v[20:21], 0, s[20:21]
	v_lshl_add_u64 v[38:39], v[18:19], 0, s[20:21]
	v_lshl_add_u64 v[40:41], v[16:17], 0, s[20:21]
	v_lshl_add_u64 v[42:43], v[14:15], 0, s[20:21]
	v_lshl_add_u64 v[44:45], v[12:13], 0, s[20:21]
	v_lshl_add_u64 v[46:47], v[10:11], 0, s[20:21]
	v_lshl_add_u64 v[48:49], v[8:9], 0, s[20:21]
	v_lshl_add_u64 v[50:51], v[6:7], 0, s[20:21]
	global_load_dword v52, v[36:37], off nt
	global_load_dword v53, v[38:39], off nt
	global_load_dword v54, v[40:41], off nt
	global_load_dword v55, v[42:43], off nt
	global_load_dword v56, v[44:45], off nt
	global_load_dword v57, v[46:47], off nt
	global_load_dword v58, v[48:49], off nt
	global_load_dword v59, v[50:51], off nt
	s_add_u32 s20, s20, 0x8000
	s_addc_u32 s21, s21, 0
	v_lshl_add_u64 v[36:37], v[20:21], 0, s[20:21]
	v_lshl_add_u64 v[38:39], v[18:19], 0, s[20:21]
	v_lshl_add_u64 v[40:41], v[16:17], 0, s[20:21]
	v_lshl_add_u64 v[42:43], v[14:15], 0, s[20:21]
	v_lshl_add_u64 v[44:45], v[12:13], 0, s[20:21]
	v_lshl_add_u64 v[46:47], v[10:11], 0, s[20:21]
	v_lshl_add_u64 v[48:49], v[8:9], 0, s[20:21]
	v_lshl_add_u64 v[50:51], v[6:7], 0, s[20:21]
	global_load_dword v60, v[36:37], off nt
	global_load_dword v61, v[38:39], off nt
	global_load_dword v62, v[40:41], off nt
	global_load_dword v63, v[42:43], off nt
	global_load_dword v64, v[44:45], off nt
	global_load_dword v65, v[46:47], off nt
	global_load_dword v66, v[48:49], off nt
	global_load_dword v67, v[50:51], off nt
	s_add_u32 s20, s20, 0x8000
	s_addc_u32 s21, s21, 0
	v_lshl_add_u64 v[36:37], v[20:21], 0, s[20:21]
	v_lshl_add_u64 v[38:39], v[18:19], 0, s[20:21]
	v_lshl_add_u64 v[40:41], v[16:17], 0, s[20:21]
	v_lshl_add_u64 v[42:43], v[14:15], 0, s[20:21]
	v_lshl_add_u64 v[44:45], v[12:13], 0, s[20:21]
	v_lshl_add_u64 v[46:47], v[10:11], 0, s[20:21]
	v_lshl_add_u64 v[48:49], v[8:9], 0, s[20:21]
	v_lshl_add_u64 v[50:51], v[6:7], 0, s[20:21]
	global_load_dword v68, v[36:37], off nt
	global_load_dword v69, v[38:39], off nt
	global_load_dword v70, v[40:41], off nt
	global_load_dword v71, v[42:43], off nt
	global_load_dword v72, v[44:45], off nt
	global_load_dword v73, v[46:47], off nt
	global_load_dword v74, v[48:49], off nt
	global_load_dword v75, v[50:51], off nt
	s_add_u32 s20, s20, 0x8000
	s_addc_u32 s21, s21, 0
	v_lshl_add_u64 v[36:37], v[20:21], 0, s[20:21]
	v_lshl_add_u64 v[38:39], v[18:19], 0, s[20:21]
	v_lshl_add_u64 v[40:41], v[16:17], 0, s[20:21]
	v_lshl_add_u64 v[42:43], v[14:15], 0, s[20:21]
	v_lshl_add_u64 v[44:45], v[12:13], 0, s[20:21]
	v_lshl_add_u64 v[46:47], v[10:11], 0, s[20:21]
	v_lshl_add_u64 v[48:49], v[8:9], 0, s[20:21]
	v_lshl_add_u64 v[50:51], v[6:7], 0, s[20:21]
	global_load_dword v76, v[36:37], off nt
	global_load_dword v77, v[38:39], off nt
	global_load_dword v78, v[40:41], off nt
	global_load_dword v79, v[42:43], off nt
	global_load_dword v80, v[44:45], off nt
	global_load_dword v81, v[46:47], off nt
	global_load_dword v82, v[48:49], off nt
	global_load_dword v83, v[50:51], off nt
	s_add_u32 s20, s20, 0x8000
	s_addc_u32 s21, s21, 0
	v_add_u32_e32 v36, 0x400, v35
	s_waitcnt vmcnt(30)
	ds_write2_b32 v35, v52, v53 offset1:66
	s_waitcnt vmcnt(28)
	ds_write2_b32 v35, v54, v55 offset0:132 offset1:198
	s_waitcnt vmcnt(26)
	ds_write2_b32 v36, v56, v57 offset0:8 offset1:74
	s_waitcnt vmcnt(24)
	ds_write2_b32 v36, v58, v59 offset0:140 offset1:206
	v_add_u32_e32 v35, 0x840, v35
	v_add_u32_e32 v36, 0x400, v35
	s_waitcnt vmcnt(22)
	ds_write2_b32 v35, v60, v61 offset1:66
	s_waitcnt vmcnt(20)
	ds_write2_b32 v35, v62, v63 offset0:132 offset1:198
	s_waitcnt vmcnt(18)
	ds_write2_b32 v36, v64, v65 offset0:8 offset1:74
	s_waitcnt vmcnt(16)
	ds_write2_b32 v36, v66, v67 offset0:140 offset1:206
	v_add_u32_e32 v35, 0x840, v35
	v_add_u32_e32 v36, 0x400, v35
	s_waitcnt vmcnt(14)
	ds_write2_b32 v35, v68, v69 offset1:66
	s_waitcnt vmcnt(12)
	ds_write2_b32 v35, v70, v71 offset0:132 offset1:198
	s_waitcnt vmcnt(10)
	ds_write2_b32 v36, v72, v73 offset0:8 offset1:74
	s_waitcnt vmcnt(8)
	ds_write2_b32 v36, v74, v75 offset0:140 offset1:206
	v_add_u32_e32 v35, 0x840, v35
	v_add_u32_e32 v36, 0x400, v35
	s_waitcnt vmcnt(6)
	ds_write2_b32 v35, v76, v77 offset1:66
	s_waitcnt vmcnt(4)
	ds_write2_b32 v35, v78, v79 offset0:132 offset1:198
	s_waitcnt vmcnt(2)
	ds_write2_b32 v36, v80, v81 offset0:8 offset1:74
	s_waitcnt vmcnt(0)
	ds_write2_b32 v36, v82, v83 offset0:140 offset1:206
	v_add_u32_e32 v35, 0x840, v35
	s_waitcnt lgkmcnt(0)
	s_lshl_b32 s20, s22, 5
	ds_read2_b32 v[10:11], v23 offset1:8
	s_and_b32 s33, s20, 0x1e0
	s_lshl_b32 s20, s23, 1
	ds_read2_b32 v[14:15], v23 offset0:33 offset1:41
	s_add_u32 s20, s30, s20
	s_addc_u32 s21, s31, 0
	ds_read2_b32 v[16:17], v23 offset0:66 offset1:74
	v_lshl_add_u64 v[6:7], s[20:21], 0, v[2:3]
	ds_read2_b32 v[18:19], v23 offset0:99 offset1:107
	v_lshl_add_u64 v[12:13], v[6:7], 0, s[38:39]
	s_waitcnt lgkmcnt(3)
	v_bfe_u32 v6, v10, 16, 1
	v_add3_u32 v6, v10, v6, s26
	s_waitcnt lgkmcnt(2)
	v_bfe_u32 v7, v14, 16, 1
	ds_read2_b32 v[20:21], v23 offset0:132 offset1:140
	v_lshrrev_b32_e32 v6, 16, v6
	v_add3_u32 v7, v14, v7, s26
	ds_read2_b32 v[36:37], v23 offset0:165 offset1:173
	v_and_or_b32 v6, v7, s27, v6
	s_waitcnt lgkmcnt(3)
	v_bfe_u32 v7, v16, 16, 1
	v_add3_u32 v7, v16, v7, s26
	s_waitcnt lgkmcnt(2)
	v_bfe_u32 v8, v18, 16, 1
	ds_read2_b32 v[38:39], v23 offset0:198 offset1:206
	v_lshrrev_b32_e32 v7, 16, v7
	v_add3_u32 v8, v18, v8, s26
	ds_read2_b32 v[40:41], v23 offset0:231 offset1:239
	v_and_or_b32 v7, v8, s27, v7
	s_waitcnt lgkmcnt(3)
	v_bfe_u32 v8, v20, 16, 1
	v_add3_u32 v8, v20, v8, s26
	s_waitcnt lgkmcnt(2)
	v_bfe_u32 v9, v36, 16, 1
	v_lshrrev_b32_e32 v8, 16, v8
	v_add3_u32 v9, v36, v9, s26
	v_and_or_b32 v8, v9, s27, v8
	s_waitcnt lgkmcnt(1)
	v_bfe_u32 v9, v38, 16, 1
	v_add3_u32 v9, v38, v9, s26
	s_waitcnt lgkmcnt(0)
	v_bfe_u32 v10, v40, 16, 1
	v_lshrrev_b32_e32 v9, 16, v9
	v_add3_u32 v10, v40, v10, s26
	v_and_or_b32 v9, v10, s27, v9
	v_or_b32_e32 v10, s33, v22
	v_lshlrev_b32_e32 v42, 10, v10
	v_mov_b32_e32 v43, v3
	v_lshl_add_u64 v[42:43], v[12:13], 0, v[42:43]
	global_store_dwordx4 v[42:43], v[6:9], off
	v_bfe_u32 v10, v41, 16, 1
	v_add3_u32 v10, v41, v10, s26
	v_bfe_u32 v6, v11, 16, 1
	v_add3_u32 v6, v11, v6, s26
	v_bfe_u32 v7, v15, 16, 1
	v_lshrrev_b32_e32 v6, 16, v6
	v_add3_u32 v7, v15, v7, s26
	v_and_or_b32 v6, v7, s27, v6
	v_bfe_u32 v7, v17, 16, 1
	v_add3_u32 v7, v17, v7, s26
	v_bfe_u32 v8, v19, 16, 1
	v_lshrrev_b32_e32 v7, 16, v7
	v_add3_u32 v8, v19, v8, s26
	v_and_or_b32 v7, v8, s27, v7
	v_bfe_u32 v8, v21, 16, 1
	v_add3_u32 v8, v21, v8, s26
	v_bfe_u32 v9, v37, 16, 1
	v_lshrrev_b32_e32 v8, 16, v8
	v_add3_u32 v9, v37, v9, s26
	v_and_or_b32 v8, v9, s27, v8
	v_bfe_u32 v9, v39, 16, 1
	v_add3_u32 v9, v39, v9, s26
	v_lshrrev_b32_e32 v9, 16, v9
	v_and_or_b32 v9, v10, s27, v9
	v_or_b32_e32 v10, s33, v24
	v_lshlrev_b32_e32 v10, 10, v10
	v_mov_b32_e32 v11, v3
	ds_read2_b32 v[14:15], v23 offset0:16 offset1:24
	v_lshl_add_u64 v[10:11], v[12:13], 0, v[10:11]
	global_store_dwordx4 v[10:11], v[6:9], off
	ds_read2_b32 v[10:11], v23 offset0:49 offset1:57
	ds_read2_b32 v[16:17], v23 offset0:82 offset1:90
	ds_read2_b32 v[18:19], v23 offset0:115 offset1:123
	s_waitcnt lgkmcnt(3)
	v_bfe_u32 v6, v14, 16, 1
	v_add3_u32 v6, v14, v6, s26
	s_waitcnt lgkmcnt(2)
	v_bfe_u32 v7, v10, 16, 1
	ds_read2_b32 v[20:21], v23 offset0:148 offset1:156
	v_lshrrev_b32_e32 v6, 16, v6
	v_add3_u32 v7, v10, v7, s26
	ds_read2_b32 v[36:37], v23 offset0:181 offset1:189
	v_and_or_b32 v6, v7, s27, v6
	s_waitcnt lgkmcnt(3)
	v_bfe_u32 v7, v16, 16, 1
	v_add3_u32 v7, v16, v7, s26
	s_waitcnt lgkmcnt(2)
	v_bfe_u32 v8, v18, 16, 1
	ds_read2_b32 v[38:39], v23 offset0:214 offset1:222
	v_lshrrev_b32_e32 v7, 16, v7
	v_add3_u32 v8, v18, v8, s26
	ds_read2_b32 v[40:41], v23 offset0:247 offset1:255
	v_and_or_b32 v7, v8, s27, v7
	s_waitcnt lgkmcnt(3)
	v_bfe_u32 v8, v20, 16, 1
	v_add3_u32 v8, v20, v8, s26
	s_waitcnt lgkmcnt(2)
	v_bfe_u32 v9, v36, 16, 1
	v_lshrrev_b32_e32 v8, 16, v8
	v_add3_u32 v9, v36, v9, s26
	v_and_or_b32 v8, v9, s27, v8
	s_waitcnt lgkmcnt(1)
	v_bfe_u32 v9, v38, 16, 1
	v_add3_u32 v9, v38, v9, s26
	s_waitcnt lgkmcnt(0)
	v_bfe_u32 v10, v40, 16, 1
	v_lshrrev_b32_e32 v9, 16, v9
	v_add3_u32 v10, v40, v10, s26
	v_and_or_b32 v9, v10, s27, v9
	v_or_b32_e32 v10, s33, v25
	v_lshlrev_b32_e32 v42, 10, v10
	v_mov_b32_e32 v43, v3
	v_lshl_add_u64 v[42:43], v[12:13], 0, v[42:43]
	global_store_dwordx4 v[42:43], v[6:9], off
	v_bfe_u32 v10, v41, 16, 1
	v_add3_u32 v10, v41, v10, s26
	v_bfe_u32 v6, v15, 16, 1
	v_add3_u32 v6, v15, v6, s26
	v_bfe_u32 v7, v11, 16, 1
	v_lshrrev_b32_e32 v6, 16, v6
	v_add3_u32 v7, v11, v7, s26
	v_and_or_b32 v6, v7, s27, v6
	v_bfe_u32 v7, v17, 16, 1
	v_add3_u32 v7, v17, v7, s26
	v_bfe_u32 v8, v19, 16, 1
	v_lshrrev_b32_e32 v7, 16, v7
	v_add3_u32 v8, v19, v8, s26
	v_and_or_b32 v7, v8, s27, v7
	v_bfe_u32 v8, v21, 16, 1
	v_add3_u32 v8, v21, v8, s26
	v_bfe_u32 v9, v37, 16, 1
	v_lshrrev_b32_e32 v8, 16, v8
	v_add3_u32 v9, v37, v9, s26
	v_and_or_b32 v8, v9, s27, v8
	v_bfe_u32 v9, v39, 16, 1
	v_add3_u32 v9, v39, v9, s26
	v_lshrrev_b32_e32 v9, 16, v9
	v_and_or_b32 v9, v10, s27, v9
	v_or_b32_e32 v10, s33, v26
	v_lshlrev_b32_e32 v10, 10, v10
	v_mov_b32_e32 v11, v3
	v_lshl_add_u64 v[10:11], v[12:13], 0, v[10:11]
	global_store_dwordx4 v[10:11], v[6:9], off
	s_waitcnt lgkmcnt(0)

.LBB0_39:
	v_lshl_add_u64 v[36:37], v[20:21], 0, s[20:21]
	v_lshl_add_u64 v[38:39], v[18:19], 0, s[20:21]
	v_lshl_add_u64 v[40:41], v[16:17], 0, s[20:21]
	v_lshl_add_u64 v[42:43], v[14:15], 0, s[20:21]
	v_lshl_add_u64 v[44:45], v[12:13], 0, s[20:21]
	v_lshl_add_u64 v[46:47], v[10:11], 0, s[20:21]
	v_lshl_add_u64 v[48:49], v[8:9], 0, s[20:21]
	v_lshl_add_u64 v[50:51], v[6:7], 0, s[20:21]
	global_load_dword v52, v[36:37], off nt
	global_load_dword v53, v[38:39], off nt
	global_load_dword v54, v[40:41], off nt
	global_load_dword v55, v[42:43], off nt
	global_load_dword v56, v[44:45], off nt
	global_load_dword v57, v[46:47], off nt
	global_load_dword v58, v[48:49], off nt
	global_load_dword v59, v[50:51], off nt
	s_add_u32 s20, s20, 0x20000
	s_addc_u32 s21, s21, 0
	v_lshl_add_u64 v[36:37], v[20:21], 0, s[20:21]
	v_lshl_add_u64 v[38:39], v[18:19], 0, s[20:21]
	v_lshl_add_u64 v[40:41], v[16:17], 0, s[20:21]
	v_lshl_add_u64 v[42:43], v[14:15], 0, s[20:21]
	v_lshl_add_u64 v[44:45], v[12:13], 0, s[20:21]
	v_lshl_add_u64 v[46:47], v[10:11], 0, s[20:21]
	v_lshl_add_u64 v[48:49], v[8:9], 0, s[20:21]
	v_lshl_add_u64 v[50:51], v[6:7], 0, s[20:21]
	global_load_dword v60, v[36:37], off nt
	global_load_dword v61, v[38:39], off nt
	global_load_dword v62, v[40:41], off nt
	global_load_dword v63, v[42:43], off nt
	global_load_dword v64, v[44:45], off nt
	global_load_dword v65, v[46:47], off nt
	global_load_dword v66, v[48:49], off nt
	global_load_dword v67, v[50:51], off nt
	s_add_u32 s20, s20, 0x20000
	s_addc_u32 s21, s21, 0
	v_lshl_add_u64 v[36:37], v[20:21], 0, s[20:21]
	v_lshl_add_u64 v[38:39], v[18:19], 0, s[20:21]
	v_lshl_add_u64 v[40:41], v[16:17], 0, s[20:21]
	v_lshl_add_u64 v[42:43], v[14:15], 0, s[20:21]
	v_lshl_add_u64 v[44:45], v[12:13], 0, s[20:21]
	v_lshl_add_u64 v[46:47], v[10:11], 0, s[20:21]
	v_lshl_add_u64 v[48:49], v[8:9], 0, s[20:21]
	v_lshl_add_u64 v[50:51], v[6:7], 0, s[20:21]
	global_load_dword v68, v[36:37], off nt
	global_load_dword v69, v[38:39], off nt
	global_load_dword v70, v[40:41], off nt
	global_load_dword v71, v[42:43], off nt
	global_load_dword v72, v[44:45], off nt
	global_load_dword v73, v[46:47], off nt
	global_load_dword v74, v[48:49], off nt
	global_load_dword v75, v[50:51], off nt
	s_add_u32 s20, s20, 0x20000
	s_addc_u32 s21, s21, 0
	v_lshl_add_u64 v[36:37], v[20:21], 0, s[20:21]
	v_lshl_add_u64 v[38:39], v[18:19], 0, s[20:21]
	v_lshl_add_u64 v[40:41], v[16:17], 0, s[20:21]
	v_lshl_add_u64 v[42:43], v[14:15], 0, s[20:21]
	v_lshl_add_u64 v[44:45], v[12:13], 0, s[20:21]
	v_lshl_add_u64 v[46:47], v[10:11], 0, s[20:21]
	v_lshl_add_u64 v[48:49], v[8:9], 0, s[20:21]
	v_lshl_add_u64 v[50:51], v[6:7], 0, s[20:21]
	global_load_dword v76, v[36:37], off nt
	global_load_dword v77, v[38:39], off nt
	global_load_dword v78, v[40:41], off nt
	global_load_dword v79, v[42:43], off nt
	global_load_dword v80, v[44:45], off nt
	global_load_dword v81, v[46:47], off nt
	global_load_dword v82, v[48:49], off nt
	global_load_dword v83, v[50:51], off nt
	s_add_u32 s20, s20, 0x20000
	s_addc_u32 s21, s21, 0
	v_add_u32_e32 v36, 0x400, v35
	s_waitcnt vmcnt(30)
	ds_write2_b32 v35, v52, v53 offset1:66
	s_waitcnt vmcnt(28)
	ds_write2_b32 v35, v54, v55 offset0:132 offset1:198
	s_waitcnt vmcnt(26)
	ds_write2_b32 v36, v56, v57 offset0:8 offset1:74
	s_waitcnt vmcnt(24)
	ds_write2_b32 v36, v58, v59 offset0:140 offset1:206
	v_add_u32_e32 v35, 0x840, v35
	v_add_u32_e32 v36, 0x400, v35
	s_waitcnt vmcnt(22)
	ds_write2_b32 v35, v60, v61 offset1:66
	s_waitcnt vmcnt(20)
	ds_write2_b32 v35, v62, v63 offset0:132 offset1:198
	s_waitcnt vmcnt(18)
	ds_write2_b32 v36, v64, v65 offset0:8 offset1:74
	s_waitcnt vmcnt(16)
	ds_write2_b32 v36, v66, v67 offset0:140 offset1:206
	v_add_u32_e32 v35, 0x840, v35
	v_add_u32_e32 v36, 0x400, v35
	s_waitcnt vmcnt(14)
	ds_write2_b32 v35, v68, v69 offset1:66
	s_waitcnt vmcnt(12)
	ds_write2_b32 v35, v70, v71 offset0:132 offset1:198
	s_waitcnt vmcnt(10)
	ds_write2_b32 v36, v72, v73 offset0:8 offset1:74
	s_waitcnt vmcnt(8)
	ds_write2_b32 v36, v74, v75 offset0:140 offset1:206
	v_add_u32_e32 v35, 0x840, v35
	v_add_u32_e32 v36, 0x400, v35
	s_waitcnt vmcnt(6)
	ds_write2_b32 v35, v76, v77 offset1:66
	s_waitcnt vmcnt(4)
	ds_write2_b32 v35, v78, v79 offset0:132 offset1:198
	s_waitcnt vmcnt(2)
	ds_write2_b32 v36, v80, v81 offset0:8 offset1:74
	s_waitcnt vmcnt(0)
	ds_write2_b32 v36, v82, v83 offset0:140 offset1:206
	v_add_u32_e32 v35, 0x840, v35
	s_waitcnt lgkmcnt(0)
	s_lshl_b32 s20, s22, 5
	ds_read2_b32 v[10:11], v23 offset1:8
	s_and_b32 s23, s20, 0x7e0
	s_lshl_b32 s19, s19, 1
	ds_read2_b32 v[14:15], v23 offset0:33 offset1:41
	s_add_u32 s20, s30, s19
	s_addc_u32 s21, s31, 0
	ds_read2_b32 v[16:17], v23 offset0:66 offset1:74
	v_lshl_add_u64 v[6:7], s[20:21], 0, v[2:3]
	ds_read2_b32 v[18:19], v23 offset0:99 offset1:107
	v_lshl_add_u64 v[12:13], v[6:7], 0, s[12:13]
	s_waitcnt lgkmcnt(3)
	v_bfe_u32 v6, v10, 16, 1
	v_add3_u32 v6, v10, v6, s26
	s_waitcnt lgkmcnt(2)
	v_bfe_u32 v7, v14, 16, 1
	ds_read2_b32 v[20:21], v23 offset0:132 offset1:140
	v_lshrrev_b32_e32 v6, 16, v6
	v_add3_u32 v7, v14, v7, s26
	ds_read2_b32 v[36:37], v23 offset0:165 offset1:173
	v_and_or_b32 v6, v7, s27, v6
	s_waitcnt lgkmcnt(3)
	v_bfe_u32 v7, v16, 16, 1
	v_add3_u32 v7, v16, v7, s26
	s_waitcnt lgkmcnt(2)
	v_bfe_u32 v8, v18, 16, 1
	ds_read2_b32 v[38:39], v23 offset0:198 offset1:206
	v_lshrrev_b32_e32 v7, 16, v7
	v_add3_u32 v8, v18, v8, s26
	ds_read2_b32 v[40:41], v23 offset0:231 offset1:239
	v_and_or_b32 v7, v8, s27, v7
	s_waitcnt lgkmcnt(3)
	v_bfe_u32 v8, v20, 16, 1
	v_add3_u32 v8, v20, v8, s26
	s_waitcnt lgkmcnt(2)
	v_bfe_u32 v9, v36, 16, 1
	v_lshrrev_b32_e32 v8, 16, v8
	v_add3_u32 v9, v36, v9, s26
	v_and_or_b32 v8, v9, s27, v8
	s_waitcnt lgkmcnt(1)
	v_bfe_u32 v9, v38, 16, 1
	v_add3_u32 v9, v38, v9, s26
	s_waitcnt lgkmcnt(0)
	v_bfe_u32 v10, v40, 16, 1
	v_lshrrev_b32_e32 v9, 16, v9
	v_add3_u32 v10, v40, v10, s26
	v_and_or_b32 v9, v10, s27, v9
	v_or_b32_e32 v10, s23, v22
	v_lshlrev_b32_e32 v42, 12, v10
	v_mov_b32_e32 v43, v3
	v_lshl_add_u64 v[42:43], v[12:13], 0, v[42:43]
	global_store_dwordx4 v[42:43], v[6:9], off
	v_bfe_u32 v10, v41, 16, 1
	v_add3_u32 v10, v41, v10, s26
	v_bfe_u32 v6, v11, 16, 1
	v_add3_u32 v6, v11, v6, s26
	v_bfe_u32 v7, v15, 16, 1
	v_lshrrev_b32_e32 v6, 16, v6
	v_add3_u32 v7, v15, v7, s26
	v_and_or_b32 v6, v7, s27, v6
	v_bfe_u32 v7, v17, 16, 1
	v_add3_u32 v7, v17, v7, s26
	v_bfe_u32 v8, v19, 16, 1
	v_lshrrev_b32_e32 v7, 16, v7
	v_add3_u32 v8, v19, v8, s26
	v_and_or_b32 v7, v8, s27, v7
	v_bfe_u32 v8, v21, 16, 1
	v_add3_u32 v8, v21, v8, s26
	v_bfe_u32 v9, v37, 16, 1
	v_lshrrev_b32_e32 v8, 16, v8
	v_add3_u32 v9, v37, v9, s26
	v_and_or_b32 v8, v9, s27, v8
	v_bfe_u32 v9, v39, 16, 1
	v_add3_u32 v9, v39, v9, s26
	v_lshrrev_b32_e32 v9, 16, v9
	v_and_or_b32 v9, v10, s27, v9
	v_or_b32_e32 v10, s23, v24
	v_lshlrev_b32_e32 v10, 12, v10
	v_mov_b32_e32 v11, v3
	ds_read2_b32 v[14:15], v23 offset0:16 offset1:24
	v_lshl_add_u64 v[10:11], v[12:13], 0, v[10:11]
	global_store_dwordx4 v[10:11], v[6:9], off
	ds_read2_b32 v[10:11], v23 offset0:49 offset1:57
	ds_read2_b32 v[16:17], v23 offset0:82 offset1:90
	ds_read2_b32 v[18:19], v23 offset0:115 offset1:123
	s_waitcnt lgkmcnt(3)
	v_bfe_u32 v6, v14, 16, 1
	v_add3_u32 v6, v14, v6, s26
	s_waitcnt lgkmcnt(2)
	v_bfe_u32 v7, v10, 16, 1
	ds_read2_b32 v[20:21], v23 offset0:148 offset1:156
	v_lshrrev_b32_e32 v6, 16, v6
	v_add3_u32 v7, v10, v7, s26
	ds_read2_b32 v[36:37], v23 offset0:181 offset1:189
	v_and_or_b32 v6, v7, s27, v6
	s_waitcnt lgkmcnt(3)
	v_bfe_u32 v7, v16, 16, 1
	v_add3_u32 v7, v16, v7, s26
	s_waitcnt lgkmcnt(2)
	v_bfe_u32 v8, v18, 16, 1
	ds_read2_b32 v[38:39], v23 offset0:214 offset1:222
	v_lshrrev_b32_e32 v7, 16, v7
	v_add3_u32 v8, v18, v8, s26
	ds_read2_b32 v[40:41], v23 offset0:247 offset1:255
	v_and_or_b32 v7, v8, s27, v7
	s_waitcnt lgkmcnt(3)
	v_bfe_u32 v8, v20, 16, 1
	v_add3_u32 v8, v20, v8, s26
	s_waitcnt lgkmcnt(2)
	v_bfe_u32 v9, v36, 16, 1
	v_lshrrev_b32_e32 v8, 16, v8
	v_add3_u32 v9, v36, v9, s26
	v_and_or_b32 v8, v9, s27, v8
	s_waitcnt lgkmcnt(1)
	v_bfe_u32 v9, v38, 16, 1
	v_add3_u32 v9, v38, v9, s26
	s_waitcnt lgkmcnt(0)
	v_bfe_u32 v10, v40, 16, 1
	v_lshrrev_b32_e32 v9, 16, v9
	v_add3_u32 v10, v40, v10, s26
	v_and_or_b32 v9, v10, s27, v9
	v_or_b32_e32 v10, s23, v25
	v_lshlrev_b32_e32 v42, 12, v10
	v_mov_b32_e32 v43, v3
	v_lshl_add_u64 v[42:43], v[12:13], 0, v[42:43]
	global_store_dwordx4 v[42:43], v[6:9], off
	v_bfe_u32 v10, v41, 16, 1
	v_add3_u32 v10, v41, v10, s26
	v_bfe_u32 v6, v15, 16, 1
	v_add3_u32 v6, v15, v6, s26
	v_bfe_u32 v7, v11, 16, 1
	v_lshrrev_b32_e32 v6, 16, v6
	v_add3_u32 v7, v11, v7, s26
	v_and_or_b32 v6, v7, s27, v6
	v_bfe_u32 v7, v17, 16, 1
	v_add3_u32 v7, v17, v7, s26
	v_bfe_u32 v8, v19, 16, 1
	v_lshrrev_b32_e32 v7, 16, v7
	v_add3_u32 v8, v19, v8, s26
	v_and_or_b32 v7, v8, s27, v7
	v_bfe_u32 v8, v21, 16, 1
	v_add3_u32 v8, v21, v8, s26
	v_bfe_u32 v9, v37, 16, 1
	v_lshrrev_b32_e32 v8, 16, v8
	v_add3_u32 v9, v37, v9, s26
	v_and_or_b32 v8, v9, s27, v8
	v_bfe_u32 v9, v39, 16, 1
	v_add3_u32 v9, v39, v9, s26
	v_lshrrev_b32_e32 v9, 16, v9
	v_and_or_b32 v9, v10, s27, v9
	v_or_b32_e32 v10, s23, v26
	v_lshlrev_b32_e32 v10, 12, v10
	v_mov_b32_e32 v11, v3
	v_lshl_add_u64 v[10:11], v[12:13], 0, v[10:11]
	global_store_dwordx4 v[10:11], v[6:9], off
	s_waitcnt lgkmcnt(0)

.LBB0_44:
	v_lshl_add_u64 v[36:37], v[20:21], 0, s[20:21]
	v_lshl_add_u64 v[38:39], v[18:19], 0, s[20:21]
	v_lshl_add_u64 v[40:41], v[16:17], 0, s[20:21]
	v_lshl_add_u64 v[42:43], v[14:15], 0, s[20:21]
	v_lshl_add_u64 v[44:45], v[12:13], 0, s[20:21]
	v_lshl_add_u64 v[46:47], v[10:11], 0, s[20:21]
	v_lshl_add_u64 v[48:49], v[8:9], 0, s[20:21]
	v_lshl_add_u64 v[50:51], v[6:7], 0, s[20:21]
	global_load_dword v52, v[36:37], off nt
	global_load_dword v53, v[38:39], off nt
	global_load_dword v54, v[40:41], off nt
	global_load_dword v55, v[42:43], off nt
	global_load_dword v56, v[44:45], off nt
	global_load_dword v57, v[46:47], off nt
	global_load_dword v58, v[48:49], off nt
	global_load_dword v59, v[50:51], off nt
	s_add_u32 s20, s20, 0x50000
	s_addc_u32 s21, s21, 0
	v_lshl_add_u64 v[36:37], v[20:21], 0, s[20:21]
	v_lshl_add_u64 v[38:39], v[18:19], 0, s[20:21]
	v_lshl_add_u64 v[40:41], v[16:17], 0, s[20:21]
	v_lshl_add_u64 v[42:43], v[14:15], 0, s[20:21]
	v_lshl_add_u64 v[44:45], v[12:13], 0, s[20:21]
	v_lshl_add_u64 v[46:47], v[10:11], 0, s[20:21]
	v_lshl_add_u64 v[48:49], v[8:9], 0, s[20:21]
	v_lshl_add_u64 v[50:51], v[6:7], 0, s[20:21]
	global_load_dword v60, v[36:37], off nt
	global_load_dword v61, v[38:39], off nt
	global_load_dword v62, v[40:41], off nt
	global_load_dword v63, v[42:43], off nt
	global_load_dword v64, v[44:45], off nt
	global_load_dword v65, v[46:47], off nt
	global_load_dword v66, v[48:49], off nt
	global_load_dword v67, v[50:51], off nt
	s_add_u32 s20, s20, 0x50000
	s_addc_u32 s21, s21, 0
	v_lshl_add_u64 v[36:37], v[20:21], 0, s[20:21]
	v_lshl_add_u64 v[38:39], v[18:19], 0, s[20:21]
	v_lshl_add_u64 v[40:41], v[16:17], 0, s[20:21]
	v_lshl_add_u64 v[42:43], v[14:15], 0, s[20:21]
	v_lshl_add_u64 v[44:45], v[12:13], 0, s[20:21]
	v_lshl_add_u64 v[46:47], v[10:11], 0, s[20:21]
	v_lshl_add_u64 v[48:49], v[8:9], 0, s[20:21]
	v_lshl_add_u64 v[50:51], v[6:7], 0, s[20:21]
	global_load_dword v68, v[36:37], off nt
	global_load_dword v69, v[38:39], off nt
	global_load_dword v70, v[40:41], off nt
	global_load_dword v71, v[42:43], off nt
	global_load_dword v72, v[44:45], off nt
	global_load_dword v73, v[46:47], off nt
	global_load_dword v74, v[48:49], off nt
	global_load_dword v75, v[50:51], off nt
	s_add_u32 s20, s20, 0x50000
	s_addc_u32 s21, s21, 0
	v_lshl_add_u64 v[36:37], v[20:21], 0, s[20:21]
	v_lshl_add_u64 v[38:39], v[18:19], 0, s[20:21]
	v_lshl_add_u64 v[40:41], v[16:17], 0, s[20:21]
	v_lshl_add_u64 v[42:43], v[14:15], 0, s[20:21]
	v_lshl_add_u64 v[44:45], v[12:13], 0, s[20:21]
	v_lshl_add_u64 v[46:47], v[10:11], 0, s[20:21]
	v_lshl_add_u64 v[48:49], v[8:9], 0, s[20:21]
	v_lshl_add_u64 v[50:51], v[6:7], 0, s[20:21]
	global_load_dword v76, v[36:37], off nt
	global_load_dword v77, v[38:39], off nt
	global_load_dword v78, v[40:41], off nt
	global_load_dword v79, v[42:43], off nt
	global_load_dword v80, v[44:45], off nt
	global_load_dword v81, v[46:47], off nt
	global_load_dword v82, v[48:49], off nt
	global_load_dword v83, v[50:51], off nt
	s_add_u32 s20, s20, 0x50000
	s_addc_u32 s21, s21, 0
	v_add_u32_e32 v36, 0x400, v35
	s_waitcnt vmcnt(30)
	ds_write2_b32 v35, v52, v53 offset1:66
	s_waitcnt vmcnt(28)
	ds_write2_b32 v35, v54, v55 offset0:132 offset1:198
	s_waitcnt vmcnt(26)
	ds_write2_b32 v36, v56, v57 offset0:8 offset1:74
	s_waitcnt vmcnt(24)
	ds_write2_b32 v36, v58, v59 offset0:140 offset1:206
	v_add_u32_e32 v35, 0x840, v35
	v_add_u32_e32 v36, 0x400, v35
	s_waitcnt vmcnt(22)
	ds_write2_b32 v35, v60, v61 offset1:66
	s_waitcnt vmcnt(20)
	ds_write2_b32 v35, v62, v63 offset0:132 offset1:198
	s_waitcnt vmcnt(18)
	ds_write2_b32 v36, v64, v65 offset0:8 offset1:74
	s_waitcnt vmcnt(16)
	ds_write2_b32 v36, v66, v67 offset0:140 offset1:206
	v_add_u32_e32 v35, 0x840, v35
	v_add_u32_e32 v36, 0x400, v35
	s_waitcnt vmcnt(14)
	ds_write2_b32 v35, v68, v69 offset1:66
	s_waitcnt vmcnt(12)
	ds_write2_b32 v35, v70, v71 offset0:132 offset1:198
	s_waitcnt vmcnt(10)
	ds_write2_b32 v36, v72, v73 offset0:8 offset1:74
	s_waitcnt vmcnt(8)
	ds_write2_b32 v36, v74, v75 offset0:140 offset1:206
	v_add_u32_e32 v35, 0x840, v35
	v_add_u32_e32 v36, 0x400, v35
	s_waitcnt vmcnt(6)
	ds_write2_b32 v35, v76, v77 offset1:66
	s_waitcnt vmcnt(4)
	ds_write2_b32 v35, v78, v79 offset0:132 offset1:198
	s_waitcnt vmcnt(2)
	ds_write2_b32 v36, v80, v81 offset0:8 offset1:74
	s_waitcnt vmcnt(0)
	ds_write2_b32 v36, v82, v83 offset0:140 offset1:206
	v_add_u32_e32 v35, 0x840, v35
	s_waitcnt lgkmcnt(0)
	s_and_b32 s19, 0xffff, s19
	ds_read2_b32 v[10:11], v23 offset1:8
	s_and_b32 s23, 0xffff, s23
	s_lshl_b32 s19, s19, 1
	ds_read2_b32 v[14:15], v23 offset0:33 offset1:41
	s_add_u32 s20, s30, s19
	s_addc_u32 s21, s31, 0
	ds_read2_b32 v[16:17], v23 offset0:66 offset1:74
	v_lshl_add_u64 v[6:7], s[20:21], 0, v[2:3]
	ds_read2_b32 v[18:19], v23 offset0:99 offset1:107
	v_lshl_add_u64 v[12:13], v[6:7], 0, s[14:15]
	s_waitcnt lgkmcnt(3)
	v_bfe_u32 v6, v10, 16, 1
	v_add3_u32 v6, v10, v6, s26
	s_waitcnt lgkmcnt(2)
	v_bfe_u32 v7, v14, 16, 1
	ds_read2_b32 v[20:21], v23 offset0:132 offset1:140
	v_lshrrev_b32_e32 v6, 16, v6
	v_add3_u32 v7, v14, v7, s26
	ds_read2_b32 v[36:37], v23 offset0:165 offset1:173
	v_and_or_b32 v6, v7, s27, v6
	s_waitcnt lgkmcnt(3)
	v_bfe_u32 v7, v16, 16, 1
	v_add3_u32 v7, v16, v7, s26
	s_waitcnt lgkmcnt(2)
	v_bfe_u32 v8, v18, 16, 1
	ds_read2_b32 v[38:39], v23 offset0:198 offset1:206
	v_lshrrev_b32_e32 v7, 16, v7
	v_add3_u32 v8, v18, v8, s26
	ds_read2_b32 v[40:41], v23 offset0:231 offset1:239
	v_and_or_b32 v7, v8, s27, v7
	s_waitcnt lgkmcnt(3)
	v_bfe_u32 v8, v20, 16, 1
	v_add3_u32 v8, v20, v8, s26
	s_waitcnt lgkmcnt(2)
	v_bfe_u32 v9, v36, 16, 1
	v_lshrrev_b32_e32 v8, 16, v8
	v_add3_u32 v9, v36, v9, s26
	v_and_or_b32 v8, v9, s27, v8
	s_waitcnt lgkmcnt(1)
	v_bfe_u32 v9, v38, 16, 1
	v_add3_u32 v9, v38, v9, s26
	s_waitcnt lgkmcnt(0)
	v_bfe_u32 v10, v40, 16, 1
	v_lshrrev_b32_e32 v9, 16, v9
	v_add3_u32 v10, v40, v10, s26
	v_and_or_b32 v9, v10, s27, v9
	v_or_b32_e32 v10, s23, v22
	v_lshlrev_b32_e32 v42, 12, v10
	v_mov_b32_e32 v43, v3
	v_lshl_add_u64 v[42:43], v[12:13], 0, v[42:43]
	global_store_dwordx4 v[42:43], v[6:9], off
	v_bfe_u32 v10, v41, 16, 1
	v_add3_u32 v10, v41, v10, s26
	v_bfe_u32 v6, v11, 16, 1
	v_add3_u32 v6, v11, v6, s26
	v_bfe_u32 v7, v15, 16, 1
	v_lshrrev_b32_e32 v6, 16, v6
	v_add3_u32 v7, v15, v7, s26
	v_and_or_b32 v6, v7, s27, v6
	v_bfe_u32 v7, v17, 16, 1
	v_add3_u32 v7, v17, v7, s26
	v_bfe_u32 v8, v19, 16, 1
	v_lshrrev_b32_e32 v7, 16, v7
	v_add3_u32 v8, v19, v8, s26
	v_and_or_b32 v7, v8, s27, v7
	v_bfe_u32 v8, v21, 16, 1
	v_add3_u32 v8, v21, v8, s26
	v_bfe_u32 v9, v37, 16, 1
	v_lshrrev_b32_e32 v8, 16, v8
	v_add3_u32 v9, v37, v9, s26
	v_and_or_b32 v8, v9, s27, v8
	v_bfe_u32 v9, v39, 16, 1
	v_add3_u32 v9, v39, v9, s26
	v_lshrrev_b32_e32 v9, 16, v9
	v_and_or_b32 v9, v10, s27, v9
	v_or_b32_e32 v10, s23, v24
	v_lshlrev_b32_e32 v10, 12, v10
	v_mov_b32_e32 v11, v3
	ds_read2_b32 v[14:15], v23 offset0:16 offset1:24
	v_lshl_add_u64 v[10:11], v[12:13], 0, v[10:11]
	global_store_dwordx4 v[10:11], v[6:9], off
	ds_read2_b32 v[10:11], v23 offset0:49 offset1:57
	ds_read2_b32 v[16:17], v23 offset0:82 offset1:90
	ds_read2_b32 v[18:19], v23 offset0:115 offset1:123
	s_waitcnt lgkmcnt(3)
	v_bfe_u32 v6, v14, 16, 1
	v_add3_u32 v6, v14, v6, s26
	s_waitcnt lgkmcnt(2)
	v_bfe_u32 v7, v10, 16, 1
	ds_read2_b32 v[20:21], v23 offset0:148 offset1:156
	v_lshrrev_b32_e32 v6, 16, v6
	v_add3_u32 v7, v10, v7, s26
	ds_read2_b32 v[36:37], v23 offset0:181 offset1:189
	v_and_or_b32 v6, v7, s27, v6
	s_waitcnt lgkmcnt(3)
	v_bfe_u32 v7, v16, 16, 1
	v_add3_u32 v7, v16, v7, s26
	s_waitcnt lgkmcnt(2)
	v_bfe_u32 v8, v18, 16, 1
	ds_read2_b32 v[38:39], v23 offset0:214 offset1:222
	v_lshrrev_b32_e32 v7, 16, v7
	v_add3_u32 v8, v18, v8, s26
	ds_read2_b32 v[40:41], v23 offset0:247 offset1:255
	v_and_or_b32 v7, v8, s27, v7
	s_waitcnt lgkmcnt(3)
	v_bfe_u32 v8, v20, 16, 1
	v_add3_u32 v8, v20, v8, s26
	s_waitcnt lgkmcnt(2)
	v_bfe_u32 v9, v36, 16, 1
	v_lshrrev_b32_e32 v8, 16, v8
	v_add3_u32 v9, v36, v9, s26
	v_and_or_b32 v8, v9, s27, v8
	s_waitcnt lgkmcnt(1)
	v_bfe_u32 v9, v38, 16, 1
	v_add3_u32 v9, v38, v9, s26
	s_waitcnt lgkmcnt(0)
	v_bfe_u32 v10, v40, 16, 1
	v_lshrrev_b32_e32 v9, 16, v9
	v_add3_u32 v10, v40, v10, s26
	v_and_or_b32 v9, v10, s27, v9
	v_or_b32_e32 v10, s23, v25
	v_lshlrev_b32_e32 v42, 12, v10
	v_mov_b32_e32 v43, v3
	v_lshl_add_u64 v[42:43], v[12:13], 0, v[42:43]
	global_store_dwordx4 v[42:43], v[6:9], off
	v_bfe_u32 v10, v41, 16, 1
	v_add3_u32 v10, v41, v10, s26
	v_bfe_u32 v6, v15, 16, 1
	v_add3_u32 v6, v15, v6, s26
	v_bfe_u32 v7, v11, 16, 1
	v_lshrrev_b32_e32 v6, 16, v6
	v_add3_u32 v7, v11, v7, s26
	v_and_or_b32 v6, v7, s27, v6
	v_bfe_u32 v7, v17, 16, 1
	v_add3_u32 v7, v17, v7, s26
	v_bfe_u32 v8, v19, 16, 1
	v_lshrrev_b32_e32 v7, 16, v7
	v_add3_u32 v8, v19, v8, s26
	v_and_or_b32 v7, v8, s27, v7
	v_bfe_u32 v8, v21, 16, 1
	v_add3_u32 v8, v21, v8, s26
	v_bfe_u32 v9, v37, 16, 1
	v_lshrrev_b32_e32 v8, 16, v8
	v_add3_u32 v9, v37, v9, s26
	v_and_or_b32 v8, v9, s27, v8
	v_bfe_u32 v9, v39, 16, 1
	v_add3_u32 v9, v39, v9, s26
	v_lshrrev_b32_e32 v9, 16, v9
	v_and_or_b32 v9, v10, s27, v9
	v_or_b32_e32 v10, s23, v26
	v_lshlrev_b32_e32 v10, 12, v10
	v_mov_b32_e32 v11, v3
	v_lshl_add_u64 v[10:11], v[12:13], 0, v[10:11]
	global_store_dwordx4 v[10:11], v[6:9], off
	s_waitcnt lgkmcnt(0)

.LBB0_49:
	v_lshl_add_u64 v[36:37], v[20:21], 0, s[20:21]
	v_lshl_add_u64 v[38:39], v[18:19], 0, s[20:21]
	v_lshl_add_u64 v[40:41], v[16:17], 0, s[20:21]
	v_lshl_add_u64 v[42:43], v[14:15], 0, s[20:21]
	v_lshl_add_u64 v[44:45], v[12:13], 0, s[20:21]
	v_lshl_add_u64 v[46:47], v[10:11], 0, s[20:21]
	v_lshl_add_u64 v[48:49], v[8:9], 0, s[20:21]
	v_lshl_add_u64 v[50:51], v[6:7], 0, s[20:21]
	global_load_dword v52, v[36:37], off nt
	global_load_dword v53, v[38:39], off nt
	global_load_dword v54, v[40:41], off nt
	global_load_dword v55, v[42:43], off nt
	global_load_dword v56, v[44:45], off nt
	global_load_dword v57, v[46:47], off nt
	global_load_dword v58, v[48:49], off nt
	global_load_dword v59, v[50:51], off nt
	s_add_u32 s20, s20, 0x20000
	s_addc_u32 s21, s21, 0
	v_lshl_add_u64 v[36:37], v[20:21], 0, s[20:21]
	v_lshl_add_u64 v[38:39], v[18:19], 0, s[20:21]
	v_lshl_add_u64 v[40:41], v[16:17], 0, s[20:21]
	v_lshl_add_u64 v[42:43], v[14:15], 0, s[20:21]
	v_lshl_add_u64 v[44:45], v[12:13], 0, s[20:21]
	v_lshl_add_u64 v[46:47], v[10:11], 0, s[20:21]
	v_lshl_add_u64 v[48:49], v[8:9], 0, s[20:21]
	v_lshl_add_u64 v[50:51], v[6:7], 0, s[20:21]
	global_load_dword v60, v[36:37], off nt
	global_load_dword v61, v[38:39], off nt
	global_load_dword v62, v[40:41], off nt
	global_load_dword v63, v[42:43], off nt
	global_load_dword v64, v[44:45], off nt
	global_load_dword v65, v[46:47], off nt
	global_load_dword v66, v[48:49], off nt
	global_load_dword v67, v[50:51], off nt
	s_add_u32 s20, s20, 0x20000
	s_addc_u32 s21, s21, 0
	v_lshl_add_u64 v[36:37], v[20:21], 0, s[20:21]
	v_lshl_add_u64 v[38:39], v[18:19], 0, s[20:21]
	v_lshl_add_u64 v[40:41], v[16:17], 0, s[20:21]
	v_lshl_add_u64 v[42:43], v[14:15], 0, s[20:21]
	v_lshl_add_u64 v[44:45], v[12:13], 0, s[20:21]
	v_lshl_add_u64 v[46:47], v[10:11], 0, s[20:21]
	v_lshl_add_u64 v[48:49], v[8:9], 0, s[20:21]
	v_lshl_add_u64 v[50:51], v[6:7], 0, s[20:21]
	global_load_dword v68, v[36:37], off nt
	global_load_dword v69, v[38:39], off nt
	global_load_dword v70, v[40:41], off nt
	global_load_dword v71, v[42:43], off nt
	global_load_dword v72, v[44:45], off nt
	global_load_dword v73, v[46:47], off nt
	global_load_dword v74, v[48:49], off nt
	global_load_dword v75, v[50:51], off nt
	s_add_u32 s20, s20, 0x20000
	s_addc_u32 s21, s21, 0
	v_lshl_add_u64 v[36:37], v[20:21], 0, s[20:21]
	v_lshl_add_u64 v[38:39], v[18:19], 0, s[20:21]
	v_lshl_add_u64 v[40:41], v[16:17], 0, s[20:21]
	v_lshl_add_u64 v[42:43], v[14:15], 0, s[20:21]
	v_lshl_add_u64 v[44:45], v[12:13], 0, s[20:21]
	v_lshl_add_u64 v[46:47], v[10:11], 0, s[20:21]
	v_lshl_add_u64 v[48:49], v[8:9], 0, s[20:21]
	v_lshl_add_u64 v[50:51], v[6:7], 0, s[20:21]
	global_load_dword v76, v[36:37], off nt
	global_load_dword v77, v[38:39], off nt
	global_load_dword v78, v[40:41], off nt
	global_load_dword v79, v[42:43], off nt
	global_load_dword v80, v[44:45], off nt
	global_load_dword v81, v[46:47], off nt
	global_load_dword v82, v[48:49], off nt
	global_load_dword v83, v[50:51], off nt
	s_add_u32 s20, s20, 0x20000
	s_addc_u32 s21, s21, 0
	v_add_u32_e32 v36, 0x400, v35
	s_waitcnt vmcnt(30)
	ds_write2_b32 v35, v52, v53 offset1:66
	s_waitcnt vmcnt(28)
	ds_write2_b32 v35, v54, v55 offset0:132 offset1:198
	s_waitcnt vmcnt(26)
	ds_write2_b32 v36, v56, v57 offset0:8 offset1:74
	s_waitcnt vmcnt(24)
	ds_write2_b32 v36, v58, v59 offset0:140 offset1:206
	v_add_u32_e32 v35, 0x840, v35
	v_add_u32_e32 v36, 0x400, v35
	s_waitcnt vmcnt(22)
	ds_write2_b32 v35, v60, v61 offset1:66
	s_waitcnt vmcnt(20)
	ds_write2_b32 v35, v62, v63 offset0:132 offset1:198
	s_waitcnt vmcnt(18)
	ds_write2_b32 v36, v64, v65 offset0:8 offset1:74
	s_waitcnt vmcnt(16)
	ds_write2_b32 v36, v66, v67 offset0:140 offset1:206
	v_add_u32_e32 v35, 0x840, v35
	v_add_u32_e32 v36, 0x400, v35
	s_waitcnt vmcnt(14)
	ds_write2_b32 v35, v68, v69 offset1:66
	s_waitcnt vmcnt(12)
	ds_write2_b32 v35, v70, v71 offset0:132 offset1:198
	s_waitcnt vmcnt(10)
	ds_write2_b32 v36, v72, v73 offset0:8 offset1:74
	s_waitcnt vmcnt(8)
	ds_write2_b32 v36, v74, v75 offset0:140 offset1:206
	v_add_u32_e32 v35, 0x840, v35
	v_add_u32_e32 v36, 0x400, v35
	s_waitcnt vmcnt(6)
	ds_write2_b32 v35, v76, v77 offset1:66
	s_waitcnt vmcnt(4)
	ds_write2_b32 v35, v78, v79 offset0:132 offset1:198
	s_waitcnt vmcnt(2)
	ds_write2_b32 v36, v80, v81 offset0:8 offset1:74
	s_waitcnt vmcnt(0)
	ds_write2_b32 v36, v82, v83 offset0:140 offset1:206
	v_add_u32_e32 v35, 0x840, v35
	s_waitcnt lgkmcnt(0)
	s_lshl_b32 s20, s22, 5
	ds_read2_b32 v[10:11], v23 offset1:8
	s_and_b32 s23, s20, 0x7e0
	s_lshl_b32 s19, s19, 1
	ds_read2_b32 v[14:15], v23 offset0:33 offset1:41
	s_add_u32 s20, s30, s19
	s_addc_u32 s21, s31, 0
	ds_read2_b32 v[16:17], v23 offset0:66 offset1:74
	v_lshl_add_u64 v[6:7], s[20:21], 0, v[2:3]
	ds_read2_b32 v[18:19], v23 offset0:99 offset1:107
	v_lshl_add_u64 v[12:13], v[6:7], 0, s[16:17]
	s_waitcnt lgkmcnt(3)
	v_bfe_u32 v6, v10, 16, 1
	v_add3_u32 v6, v10, v6, s26
	s_waitcnt lgkmcnt(2)
	v_bfe_u32 v7, v14, 16, 1
	ds_read2_b32 v[20:21], v23 offset0:132 offset1:140
	v_lshrrev_b32_e32 v6, 16, v6
	v_add3_u32 v7, v14, v7, s26
	ds_read2_b32 v[36:37], v23 offset0:165 offset1:173
	v_and_or_b32 v6, v7, s27, v6
	s_waitcnt lgkmcnt(3)
	v_bfe_u32 v7, v16, 16, 1
	v_add3_u32 v7, v16, v7, s26
	s_waitcnt lgkmcnt(2)
	v_bfe_u32 v8, v18, 16, 1
	ds_read2_b32 v[38:39], v23 offset0:198 offset1:206
	v_lshrrev_b32_e32 v7, 16, v7
	v_add3_u32 v8, v18, v8, s26
	ds_read2_b32 v[40:41], v23 offset0:231 offset1:239
	v_and_or_b32 v7, v8, s27, v7
	s_waitcnt lgkmcnt(3)
	v_bfe_u32 v8, v20, 16, 1
	v_add3_u32 v8, v20, v8, s26
	s_waitcnt lgkmcnt(2)
	v_bfe_u32 v9, v36, 16, 1
	v_lshrrev_b32_e32 v8, 16, v8
	v_add3_u32 v9, v36, v9, s26
	v_and_or_b32 v8, v9, s27, v8
	s_waitcnt lgkmcnt(1)
	v_bfe_u32 v9, v38, 16, 1
	v_add3_u32 v9, v38, v9, s26
	s_waitcnt lgkmcnt(0)
	v_bfe_u32 v10, v40, 16, 1
	v_lshrrev_b32_e32 v9, 16, v9
	v_add3_u32 v10, v40, v10, s26
	v_and_or_b32 v9, v10, s27, v9
	v_or_b32_e32 v10, s23, v22
	v_mul_u32_u24_e32 v10, 0x1600, v10
	v_lshlrev_b32_e32 v42, 1, v10
	v_mov_b32_e32 v43, v3
	v_lshl_add_u64 v[42:43], v[12:13], 0, v[42:43]
	global_store_dwordx4 v[42:43], v[6:9], off
	v_bfe_u32 v10, v41, 16, 1
	v_add3_u32 v10, v41, v10, s26
	v_bfe_u32 v6, v11, 16, 1
	v_add3_u32 v6, v11, v6, s26
	v_bfe_u32 v7, v15, 16, 1
	v_lshrrev_b32_e32 v6, 16, v6
	v_add3_u32 v7, v15, v7, s26
	v_and_or_b32 v6, v7, s27, v6
	v_bfe_u32 v7, v17, 16, 1
	v_add3_u32 v7, v17, v7, s26
	v_bfe_u32 v8, v19, 16, 1
	v_lshrrev_b32_e32 v7, 16, v7
	v_add3_u32 v8, v19, v8, s26
	v_and_or_b32 v7, v8, s27, v7
	v_bfe_u32 v8, v21, 16, 1
	v_add3_u32 v8, v21, v8, s26
	v_bfe_u32 v9, v37, 16, 1
	v_lshrrev_b32_e32 v8, 16, v8
	v_add3_u32 v9, v37, v9, s26
	v_and_or_b32 v8, v9, s27, v8
	v_bfe_u32 v9, v39, 16, 1
	v_add3_u32 v9, v39, v9, s26
	v_lshrrev_b32_e32 v9, 16, v9
	v_and_or_b32 v9, v10, s27, v9
	v_or_b32_e32 v10, s23, v24
	v_mul_u32_u24_e32 v10, 0x1600, v10
	v_lshlrev_b32_e32 v10, 1, v10
	v_mov_b32_e32 v11, v3
	ds_read2_b32 v[14:15], v23 offset0:16 offset1:24
	v_lshl_add_u64 v[10:11], v[12:13], 0, v[10:11]
	global_store_dwordx4 v[10:11], v[6:9], off
	ds_read2_b32 v[10:11], v23 offset0:49 offset1:57
	ds_read2_b32 v[16:17], v23 offset0:82 offset1:90
	ds_read2_b32 v[18:19], v23 offset0:115 offset1:123
	s_waitcnt lgkmcnt(3)
	v_bfe_u32 v6, v14, 16, 1
	v_add3_u32 v6, v14, v6, s26
	s_waitcnt lgkmcnt(2)
	v_bfe_u32 v7, v10, 16, 1
	ds_read2_b32 v[20:21], v23 offset0:148 offset1:156
	v_lshrrev_b32_e32 v6, 16, v6
	v_add3_u32 v7, v10, v7, s26
	ds_read2_b32 v[36:37], v23 offset0:181 offset1:189
	v_and_or_b32 v6, v7, s27, v6
	s_waitcnt lgkmcnt(3)
	v_bfe_u32 v7, v16, 16, 1
	v_add3_u32 v7, v16, v7, s26
	s_waitcnt lgkmcnt(2)
	v_bfe_u32 v8, v18, 16, 1
	ds_read2_b32 v[38:39], v23 offset0:214 offset1:222
	v_lshrrev_b32_e32 v7, 16, v7
	v_add3_u32 v8, v18, v8, s26
	ds_read2_b32 v[40:41], v23 offset0:247 offset1:255
	v_and_or_b32 v7, v8, s27, v7
	s_waitcnt lgkmcnt(3)
	v_bfe_u32 v8, v20, 16, 1
	v_add3_u32 v8, v20, v8, s26
	s_waitcnt lgkmcnt(2)
	v_bfe_u32 v9, v36, 16, 1
	v_lshrrev_b32_e32 v8, 16, v8
	v_add3_u32 v9, v36, v9, s26
	v_and_or_b32 v8, v9, s27, v8
	s_waitcnt lgkmcnt(1)
	v_bfe_u32 v9, v38, 16, 1
	v_add3_u32 v9, v38, v9, s26
	s_waitcnt lgkmcnt(0)
	v_bfe_u32 v10, v40, 16, 1
	v_lshrrev_b32_e32 v9, 16, v9
	v_add3_u32 v10, v40, v10, s26
	v_and_or_b32 v9, v10, s27, v9
	v_or_b32_e32 v10, s23, v25
	v_mul_u32_u24_e32 v10, 0x1600, v10
	v_lshlrev_b32_e32 v42, 1, v10
	v_mov_b32_e32 v43, v3
	v_lshl_add_u64 v[42:43], v[12:13], 0, v[42:43]
	global_store_dwordx4 v[42:43], v[6:9], off
	v_bfe_u32 v10, v41, 16, 1
	v_add3_u32 v10, v41, v10, s26
	v_bfe_u32 v6, v15, 16, 1
	v_add3_u32 v6, v15, v6, s26
	v_bfe_u32 v7, v11, 16, 1
	v_lshrrev_b32_e32 v6, 16, v6
	v_add3_u32 v7, v11, v7, s26
	v_and_or_b32 v6, v7, s27, v6
	v_bfe_u32 v7, v17, 16, 1
	v_add3_u32 v7, v17, v7, s26
	v_bfe_u32 v8, v19, 16, 1
	v_lshrrev_b32_e32 v7, 16, v7
	v_add3_u32 v8, v19, v8, s26
	v_and_or_b32 v7, v8, s27, v7
	v_bfe_u32 v8, v21, 16, 1
	v_add3_u32 v8, v21, v8, s26
	v_bfe_u32 v9, v37, 16, 1
	v_lshrrev_b32_e32 v8, 16, v8
	v_add3_u32 v9, v37, v9, s26
	v_and_or_b32 v8, v9, s27, v8
	v_bfe_u32 v9, v39, 16, 1
	v_add3_u32 v9, v39, v9, s26
	v_lshrrev_b32_e32 v9, 16, v9
	v_and_or_b32 v9, v10, s27, v9
	v_or_b32_e32 v10, s23, v26
	v_mul_u32_u24_e32 v10, 0x1600, v10
	v_lshlrev_b32_e32 v10, 1, v10
	v_mov_b32_e32 v11, v3
	v_lshl_add_u64 v[10:11], v[12:13], 0, v[10:11]
	global_store_dwordx4 v[10:11], v[6:9], off
	s_waitcnt lgkmcnt(0)

.LBB0_54:
	v_lshl_add_u64 v[36:37], v[20:21], 0, s[20:21]
	v_lshl_add_u64 v[38:39], v[18:19], 0, s[20:21]
	v_lshl_add_u64 v[40:41], v[16:17], 0, s[20:21]
	v_lshl_add_u64 v[42:43], v[14:15], 0, s[20:21]
	v_lshl_add_u64 v[44:45], v[12:13], 0, s[20:21]
	v_lshl_add_u64 v[46:47], v[10:11], 0, s[20:21]
	v_lshl_add_u64 v[48:49], v[8:9], 0, s[20:21]
	v_lshl_add_u64 v[50:51], v[6:7], 0, s[20:21]
	global_load_dword v52, v[36:37], off nt
	global_load_dword v53, v[38:39], off nt
	global_load_dword v54, v[40:41], off nt
	global_load_dword v55, v[42:43], off nt
	global_load_dword v56, v[44:45], off nt
	global_load_dword v57, v[46:47], off nt
	global_load_dword v58, v[48:49], off nt
	global_load_dword v59, v[50:51], off nt
	s_add_u32 s20, s20, 0x58000
	s_addc_u32 s21, s21, 0
	v_lshl_add_u64 v[36:37], v[20:21], 0, s[20:21]
	v_lshl_add_u64 v[38:39], v[18:19], 0, s[20:21]
	v_lshl_add_u64 v[40:41], v[16:17], 0, s[20:21]
	v_lshl_add_u64 v[42:43], v[14:15], 0, s[20:21]
	v_lshl_add_u64 v[44:45], v[12:13], 0, s[20:21]
	v_lshl_add_u64 v[46:47], v[10:11], 0, s[20:21]
	v_lshl_add_u64 v[48:49], v[8:9], 0, s[20:21]
	v_lshl_add_u64 v[50:51], v[6:7], 0, s[20:21]
	global_load_dword v60, v[36:37], off nt
	global_load_dword v61, v[38:39], off nt
	global_load_dword v62, v[40:41], off nt
	global_load_dword v63, v[42:43], off nt
	global_load_dword v64, v[44:45], off nt
	global_load_dword v65, v[46:47], off nt
	global_load_dword v66, v[48:49], off nt
	global_load_dword v67, v[50:51], off nt
	s_add_u32 s20, s20, 0x58000
	s_addc_u32 s21, s21, 0
	v_lshl_add_u64 v[36:37], v[20:21], 0, s[20:21]
	v_lshl_add_u64 v[38:39], v[18:19], 0, s[20:21]
	v_lshl_add_u64 v[40:41], v[16:17], 0, s[20:21]
	v_lshl_add_u64 v[42:43], v[14:15], 0, s[20:21]
	v_lshl_add_u64 v[44:45], v[12:13], 0, s[20:21]
	v_lshl_add_u64 v[46:47], v[10:11], 0, s[20:21]
	v_lshl_add_u64 v[48:49], v[8:9], 0, s[20:21]
	v_lshl_add_u64 v[50:51], v[6:7], 0, s[20:21]
	global_load_dword v68, v[36:37], off nt
	global_load_dword v69, v[38:39], off nt
	global_load_dword v70, v[40:41], off nt
	global_load_dword v71, v[42:43], off nt
	global_load_dword v72, v[44:45], off nt
	global_load_dword v73, v[46:47], off nt
	global_load_dword v74, v[48:49], off nt
	global_load_dword v75, v[50:51], off nt
	s_add_u32 s20, s20, 0x58000
	s_addc_u32 s21, s21, 0
	v_lshl_add_u64 v[36:37], v[20:21], 0, s[20:21]
	v_lshl_add_u64 v[38:39], v[18:19], 0, s[20:21]
	v_lshl_add_u64 v[40:41], v[16:17], 0, s[20:21]
	v_lshl_add_u64 v[42:43], v[14:15], 0, s[20:21]
	v_lshl_add_u64 v[44:45], v[12:13], 0, s[20:21]
	v_lshl_add_u64 v[46:47], v[10:11], 0, s[20:21]
	v_lshl_add_u64 v[48:49], v[8:9], 0, s[20:21]
	v_lshl_add_u64 v[50:51], v[6:7], 0, s[20:21]
	global_load_dword v76, v[36:37], off nt
	global_load_dword v77, v[38:39], off nt
	global_load_dword v78, v[40:41], off nt
	global_load_dword v79, v[42:43], off nt
	global_load_dword v80, v[44:45], off nt
	global_load_dword v81, v[46:47], off nt
	global_load_dword v82, v[48:49], off nt
	global_load_dword v83, v[50:51], off nt
	s_add_u32 s20, s20, 0x58000
	s_addc_u32 s21, s21, 0
	v_add_u32_e32 v36, 0x400, v35
	s_waitcnt vmcnt(30)
	ds_write2_b32 v35, v52, v53 offset1:66
	s_waitcnt vmcnt(28)
	ds_write2_b32 v35, v54, v55 offset0:132 offset1:198
	s_waitcnt vmcnt(26)
	ds_write2_b32 v36, v56, v57 offset0:8 offset1:74
	s_waitcnt vmcnt(24)
	ds_write2_b32 v36, v58, v59 offset0:140 offset1:206
	v_add_u32_e32 v35, 0x840, v35
	v_add_u32_e32 v36, 0x400, v35
	s_waitcnt vmcnt(22)
	ds_write2_b32 v35, v60, v61 offset1:66
	s_waitcnt vmcnt(20)
	ds_write2_b32 v35, v62, v63 offset0:132 offset1:198
	s_waitcnt vmcnt(18)
	ds_write2_b32 v36, v64, v65 offset0:8 offset1:74
	s_waitcnt vmcnt(16)
	ds_write2_b32 v36, v66, v67 offset0:140 offset1:206
	v_add_u32_e32 v35, 0x840, v35
	v_add_u32_e32 v36, 0x400, v35
	s_waitcnt vmcnt(14)
	ds_write2_b32 v35, v68, v69 offset1:66
	s_waitcnt vmcnt(12)
	ds_write2_b32 v35, v70, v71 offset0:132 offset1:198
	s_waitcnt vmcnt(10)
	ds_write2_b32 v36, v72, v73 offset0:8 offset1:74
	s_waitcnt vmcnt(8)
	ds_write2_b32 v36, v74, v75 offset0:140 offset1:206
	v_add_u32_e32 v35, 0x840, v35
	v_add_u32_e32 v36, 0x400, v35
	s_waitcnt vmcnt(6)
	ds_write2_b32 v35, v76, v77 offset1:66
	s_waitcnt vmcnt(4)
	ds_write2_b32 v35, v78, v79 offset0:132 offset1:198
	s_waitcnt vmcnt(2)
	ds_write2_b32 v36, v80, v81 offset0:8 offset1:74
	s_waitcnt vmcnt(0)
	ds_write2_b32 v36, v82, v83 offset0:140 offset1:206
	v_add_u32_e32 v35, 0x840, v35
	s_waitcnt lgkmcnt(0)
	ds_read2_b32 v[10:11], v23 offset1:8
	ds_read2_b32 v[14:15], v23 offset0:33 offset1:41
	ds_read2_b32 v[16:17], v23 offset0:66 offset1:74
	ds_read2_b32 v[18:19], v23 offset0:99 offset1:107
	ds_read2_b32 v[20:21], v23 offset0:132 offset1:140
	s_waitcnt lgkmcnt(4)
	v_bfe_u32 v6, v10, 16, 1
	v_add3_u32 v6, v10, v6, s26
	s_waitcnt lgkmcnt(3)
	v_bfe_u32 v7, v14, 16, 1
	v_lshrrev_b32_e32 v6, 16, v6
	v_add3_u32 v7, v14, v7, s26
	ds_read2_b32 v[36:37], v23 offset0:165 offset1:173
	v_and_or_b32 v6, v7, s27, v6
	s_waitcnt lgkmcnt(3)
	v_bfe_u32 v7, v16, 16, 1
	v_add3_u32 v7, v16, v7, s26
	s_waitcnt lgkmcnt(2)
	v_bfe_u32 v8, v18, 16, 1
	ds_read2_b32 v[38:39], v23 offset0:198 offset1:206
	v_lshrrev_b32_e32 v7, 16, v7
	v_add3_u32 v8, v18, v8, s26
	ds_read2_b32 v[40:41], v23 offset0:231 offset1:239
	v_and_or_b32 v7, v8, s27, v7
	s_waitcnt lgkmcnt(3)
	v_bfe_u32 v8, v20, 16, 1
	s_lshl_b32 s20, s23, 5
	s_lshl_b32 s21, s23, 6
	v_add3_u32 v8, v20, v8, s26
	s_waitcnt lgkmcnt(2)
	v_bfe_u32 v9, v36, 16, 1
	s_and_b32 s21, s21, 0x3f00
	s_and_b32 s20, s20, 0x60
	v_lshrrev_b32_e32 v8, 16, v8
	v_add3_u32 v9, v36, v9, s26
	s_or_b32 s20, s21, s20
	s_and_b32 s19, 0xffff, s19
	v_and_or_b32 v8, v9, s27, v8
	s_waitcnt lgkmcnt(1)
	v_bfe_u32 v9, v38, 16, 1
	s_or_b32 s23, s20, 0x80
	s_lshl_b32 s19, s19, 1
	v_add3_u32 v9, v38, v9, s26
	s_waitcnt lgkmcnt(0)
	v_bfe_u32 v10, v40, 16, 1
	s_add_u32 s20, s30, s19
	v_lshrrev_b32_e32 v9, 16, v9
	v_add3_u32 v10, v40, v10, s26
	s_addc_u32 s21, s31, 0
	v_and_or_b32 v9, v10, s27, v9
	v_or_b32_e32 v10, s23, v22
	v_lshl_add_u64 v[12:13], s[20:21], 0, v[2:3]
	v_lshlrev_b32_e32 v42, 12, v10
	v_mov_b32_e32 v43, v3
	v_lshl_add_u64 v[42:43], v[12:13], 0, v[42:43]
	global_store_dwordx4 v[42:43], v[6:9], off
	v_bfe_u32 v10, v41, 16, 1
	v_add3_u32 v10, v41, v10, s26
	v_bfe_u32 v6, v11, 16, 1
	v_add3_u32 v6, v11, v6, s26
	v_bfe_u32 v7, v15, 16, 1
	v_lshrrev_b32_e32 v6, 16, v6
	v_add3_u32 v7, v15, v7, s26
	v_and_or_b32 v6, v7, s27, v6
	v_bfe_u32 v7, v17, 16, 1
	v_add3_u32 v7, v17, v7, s26
	v_bfe_u32 v8, v19, 16, 1
	v_lshrrev_b32_e32 v7, 16, v7
	v_add3_u32 v8, v19, v8, s26
	v_and_or_b32 v7, v8, s27, v7
	v_bfe_u32 v8, v21, 16, 1
	v_add3_u32 v8, v21, v8, s26
	v_bfe_u32 v9, v37, 16, 1
	v_lshrrev_b32_e32 v8, 16, v8
	v_add3_u32 v9, v37, v9, s26
	v_and_or_b32 v8, v9, s27, v8
	v_bfe_u32 v9, v39, 16, 1
	v_add3_u32 v9, v39, v9, s26
	v_lshrrev_b32_e32 v9, 16, v9
	v_and_or_b32 v9, v10, s27, v9
	v_or_b32_e32 v10, s23, v24
	v_lshlrev_b32_e32 v10, 12, v10
	v_mov_b32_e32 v11, v3
	ds_read2_b32 v[14:15], v23 offset0:16 offset1:24
	v_lshl_add_u64 v[10:11], v[12:13], 0, v[10:11]
	global_store_dwordx4 v[10:11], v[6:9], off
	ds_read2_b32 v[10:11], v23 offset0:49 offset1:57
	ds_read2_b32 v[16:17], v23 offset0:82 offset1:90
	ds_read2_b32 v[18:19], v23 offset0:115 offset1:123
	s_waitcnt lgkmcnt(3)
	v_bfe_u32 v6, v14, 16, 1
	v_add3_u32 v6, v14, v6, s26
	s_waitcnt lgkmcnt(2)
	v_bfe_u32 v7, v10, 16, 1
	ds_read2_b32 v[20:21], v23 offset0:148 offset1:156
	v_lshrrev_b32_e32 v6, 16, v6
	v_add3_u32 v7, v10, v7, s26
	ds_read2_b32 v[36:37], v23 offset0:181 offset1:189
	v_and_or_b32 v6, v7, s27, v6
	s_waitcnt lgkmcnt(3)
	v_bfe_u32 v7, v16, 16, 1
	v_add3_u32 v7, v16, v7, s26
	s_waitcnt lgkmcnt(2)
	v_bfe_u32 v8, v18, 16, 1
	ds_read2_b32 v[38:39], v23 offset0:214 offset1:222
	v_lshrrev_b32_e32 v7, 16, v7
	v_add3_u32 v8, v18, v8, s26
	ds_read2_b32 v[40:41], v23 offset0:247 offset1:255
	v_and_or_b32 v7, v8, s27, v7
	s_waitcnt lgkmcnt(3)
	v_bfe_u32 v8, v20, 16, 1
	v_add3_u32 v8, v20, v8, s26
	s_waitcnt lgkmcnt(2)
	v_bfe_u32 v9, v36, 16, 1
	v_lshrrev_b32_e32 v8, 16, v8
	v_add3_u32 v9, v36, v9, s26
	v_and_or_b32 v8, v9, s27, v8
	s_waitcnt lgkmcnt(1)
	v_bfe_u32 v9, v38, 16, 1
	v_add3_u32 v9, v38, v9, s26
	s_waitcnt lgkmcnt(0)
	v_bfe_u32 v10, v40, 16, 1
	v_lshrrev_b32_e32 v9, 16, v9
	v_add3_u32 v10, v40, v10, s26
	v_and_or_b32 v9, v10, s27, v9
	v_or_b32_e32 v10, s23, v25
	v_lshlrev_b32_e32 v42, 12, v10
	v_mov_b32_e32 v43, v3
	v_lshl_add_u64 v[42:43], v[12:13], 0, v[42:43]
	global_store_dwordx4 v[42:43], v[6:9], off
	v_bfe_u32 v10, v41, 16, 1
	v_add3_u32 v10, v41, v10, s26
	v_bfe_u32 v6, v15, 16, 1
	v_add3_u32 v6, v15, v6, s26
	v_bfe_u32 v7, v11, 16, 1
	v_lshrrev_b32_e32 v6, 16, v6
	v_add3_u32 v7, v11, v7, s26
	v_and_or_b32 v6, v7, s27, v6
	v_bfe_u32 v7, v17, 16, 1
	v_add3_u32 v7, v17, v7, s26
	v_bfe_u32 v8, v19, 16, 1
	v_lshrrev_b32_e32 v7, 16, v7
	v_add3_u32 v8, v19, v8, s26
	v_and_or_b32 v7, v8, s27, v7
	v_bfe_u32 v8, v21, 16, 1
	v_add3_u32 v8, v21, v8, s26
	v_bfe_u32 v9, v37, 16, 1
	v_lshrrev_b32_e32 v8, 16, v8
	v_add3_u32 v9, v37, v9, s26
	v_and_or_b32 v8, v9, s27, v8
	v_bfe_u32 v9, v39, 16, 1
	v_add3_u32 v9, v39, v9, s26
	v_lshrrev_b32_e32 v9, 16, v9
	v_and_or_b32 v9, v10, s27, v9
	v_or_b32_e32 v10, s23, v26
	v_lshlrev_b32_e32 v10, 12, v10
	v_mov_b32_e32 v11, v3
	v_lshl_add_u64 v[10:11], v[12:13], 0, v[10:11]
	global_store_dwordx4 v[10:11], v[6:9], off
	s_waitcnt lgkmcnt(0)

.LBB0_59:
	v_lshl_add_u64 v[36:37], v[20:21], 0, s[22:23]
	v_lshl_add_u64 v[38:39], v[18:19], 0, s[22:23]
	v_lshl_add_u64 v[40:41], v[16:17], 0, s[22:23]
	v_lshl_add_u64 v[42:43], v[14:15], 0, s[22:23]
	v_lshl_add_u64 v[44:45], v[12:13], 0, s[22:23]
	v_lshl_add_u64 v[46:47], v[10:11], 0, s[22:23]
	v_lshl_add_u64 v[48:49], v[8:9], 0, s[22:23]
	v_lshl_add_u64 v[50:51], v[6:7], 0, s[22:23]
	global_load_dword v52, v[36:37], off nt
	global_load_dword v53, v[38:39], off nt
	global_load_dword v54, v[40:41], off nt
	global_load_dword v55, v[42:43], off nt
	global_load_dword v56, v[44:45], off nt
	global_load_dword v57, v[46:47], off nt
	global_load_dword v58, v[48:49], off nt
	global_load_dword v59, v[50:51], off nt
	s_add_u32 s22, s22, 0x58000
	s_addc_u32 s23, s23, 0
	v_lshl_add_u64 v[36:37], v[20:21], 0, s[22:23]
	v_lshl_add_u64 v[38:39], v[18:19], 0, s[22:23]
	v_lshl_add_u64 v[40:41], v[16:17], 0, s[22:23]
	v_lshl_add_u64 v[42:43], v[14:15], 0, s[22:23]
	v_lshl_add_u64 v[44:45], v[12:13], 0, s[22:23]
	v_lshl_add_u64 v[46:47], v[10:11], 0, s[22:23]
	v_lshl_add_u64 v[48:49], v[8:9], 0, s[22:23]
	v_lshl_add_u64 v[50:51], v[6:7], 0, s[22:23]
	global_load_dword v60, v[36:37], off nt
	global_load_dword v61, v[38:39], off nt
	global_load_dword v62, v[40:41], off nt
	global_load_dword v63, v[42:43], off nt
	global_load_dword v64, v[44:45], off nt
	global_load_dword v65, v[46:47], off nt
	global_load_dword v66, v[48:49], off nt
	global_load_dword v67, v[50:51], off nt
	s_add_u32 s22, s22, 0x58000
	s_addc_u32 s23, s23, 0
	v_lshl_add_u64 v[36:37], v[20:21], 0, s[22:23]
	v_lshl_add_u64 v[38:39], v[18:19], 0, s[22:23]
	v_lshl_add_u64 v[40:41], v[16:17], 0, s[22:23]
	v_lshl_add_u64 v[42:43], v[14:15], 0, s[22:23]
	v_lshl_add_u64 v[44:45], v[12:13], 0, s[22:23]
	v_lshl_add_u64 v[46:47], v[10:11], 0, s[22:23]
	v_lshl_add_u64 v[48:49], v[8:9], 0, s[22:23]
	v_lshl_add_u64 v[50:51], v[6:7], 0, s[22:23]
	global_load_dword v68, v[36:37], off nt
	global_load_dword v69, v[38:39], off nt
	global_load_dword v70, v[40:41], off nt
	global_load_dword v71, v[42:43], off nt
	global_load_dword v72, v[44:45], off nt
	global_load_dword v73, v[46:47], off nt
	global_load_dword v74, v[48:49], off nt
	global_load_dword v75, v[50:51], off nt
	s_add_u32 s22, s22, 0x58000
	s_addc_u32 s23, s23, 0
	v_lshl_add_u64 v[36:37], v[20:21], 0, s[22:23]
	v_lshl_add_u64 v[38:39], v[18:19], 0, s[22:23]
	v_lshl_add_u64 v[40:41], v[16:17], 0, s[22:23]
	v_lshl_add_u64 v[42:43], v[14:15], 0, s[22:23]
	v_lshl_add_u64 v[44:45], v[12:13], 0, s[22:23]
	v_lshl_add_u64 v[46:47], v[10:11], 0, s[22:23]
	v_lshl_add_u64 v[48:49], v[8:9], 0, s[22:23]
	v_lshl_add_u64 v[50:51], v[6:7], 0, s[22:23]
	global_load_dword v76, v[36:37], off nt
	global_load_dword v77, v[38:39], off nt
	global_load_dword v78, v[40:41], off nt
	global_load_dword v79, v[42:43], off nt
	global_load_dword v80, v[44:45], off nt
	global_load_dword v81, v[46:47], off nt
	global_load_dword v82, v[48:49], off nt
	global_load_dword v83, v[50:51], off nt
	s_add_u32 s22, s22, 0x58000
	s_addc_u32 s23, s23, 0
	v_add_u32_e32 v36, 0x400, v35
	s_waitcnt vmcnt(30)
	ds_write2_b32 v35, v52, v53 offset1:66
	s_waitcnt vmcnt(28)
	ds_write2_b32 v35, v54, v55 offset0:132 offset1:198
	s_waitcnt vmcnt(26)
	ds_write2_b32 v36, v56, v57 offset0:8 offset1:74
	s_waitcnt vmcnt(24)
	ds_write2_b32 v36, v58, v59 offset0:140 offset1:206
	v_add_u32_e32 v35, 0x840, v35
	v_add_u32_e32 v36, 0x400, v35
	s_waitcnt vmcnt(22)
	ds_write2_b32 v35, v60, v61 offset1:66
	s_waitcnt vmcnt(20)
	ds_write2_b32 v35, v62, v63 offset0:132 offset1:198
	s_waitcnt vmcnt(18)
	ds_write2_b32 v36, v64, v65 offset0:8 offset1:74
	s_waitcnt vmcnt(16)
	ds_write2_b32 v36, v66, v67 offset0:140 offset1:206
	v_add_u32_e32 v35, 0x840, v35
	v_add_u32_e32 v36, 0x400, v35
	s_waitcnt vmcnt(14)
	ds_write2_b32 v35, v68, v69 offset1:66
	s_waitcnt vmcnt(12)
	ds_write2_b32 v35, v70, v71 offset0:132 offset1:198
	s_waitcnt vmcnt(10)
	ds_write2_b32 v36, v72, v73 offset0:8 offset1:74
	s_waitcnt vmcnt(8)
	ds_write2_b32 v36, v74, v75 offset0:140 offset1:206
	v_add_u32_e32 v35, 0x840, v35
	v_add_u32_e32 v36, 0x400, v35
	s_waitcnt vmcnt(6)
	ds_write2_b32 v35, v76, v77 offset1:66
	s_waitcnt vmcnt(4)
	ds_write2_b32 v35, v78, v79 offset0:132 offset1:198
	s_waitcnt vmcnt(2)
	ds_write2_b32 v36, v80, v81 offset0:8 offset1:74
	s_waitcnt vmcnt(0)
	ds_write2_b32 v36, v82, v83 offset0:140 offset1:206
	v_add_u32_e32 v35, 0x840, v35
	s_waitcnt lgkmcnt(0)
	ds_read2_b32 v[10:11], v23 offset1:8
	ds_read2_b32 v[14:15], v23 offset0:33 offset1:41
	ds_read2_b32 v[16:17], v23 offset0:66 offset1:74
	ds_read2_b32 v[18:19], v23 offset0:99 offset1:107
	ds_read2_b32 v[20:21], v23 offset0:132 offset1:140
	s_waitcnt lgkmcnt(4)
	v_bfe_u32 v6, v10, 16, 1
	v_add3_u32 v6, v10, v6, s26
	s_waitcnt lgkmcnt(3)
	v_bfe_u32 v7, v14, 16, 1
	v_lshrrev_b32_e32 v6, 16, v6
	v_add3_u32 v7, v14, v7, s26
	ds_read2_b32 v[36:37], v23 offset0:165 offset1:173
	v_and_or_b32 v6, v7, s27, v6
	s_waitcnt lgkmcnt(3)
	v_bfe_u32 v7, v16, 16, 1
	v_add3_u32 v7, v16, v7, s26
	s_waitcnt lgkmcnt(2)
	v_bfe_u32 v8, v18, 16, 1
	ds_read2_b32 v[38:39], v23 offset0:198 offset1:206
	s_lshl_b32 s19, s19, 6
	v_lshrrev_b32_e32 v7, 16, v7
	v_add3_u32 v8, v18, v8, s26
	ds_read2_b32 v[40:41], v23 offset0:231 offset1:239
	s_and_b32 s19, s19, 0xffffff00
	s_and_b32 s20, s20, 0x60
	v_and_or_b32 v7, v8, s27, v7
	s_waitcnt lgkmcnt(3)
	v_bfe_u32 v8, v20, 16, 1
	s_or_b32 s20, s20, s19
	s_ashr_i32 s19, s18, 31
	v_add3_u32 v8, v20, v8, s26
	s_waitcnt lgkmcnt(2)
	v_bfe_u32 v9, v36, 16, 1
	s_lshl_b64 s[18:19], s[18:19], 1
	v_lshrrev_b32_e32 v8, 16, v8
	v_add3_u32 v9, v36, v9, s26
	s_add_u32 s18, s30, s18
	v_and_or_b32 v8, v9, s27, v8
	s_waitcnt lgkmcnt(1)
	v_bfe_u32 v9, v38, 16, 1
	v_or_b32_e32 v42, s20, v22
	s_addc_u32 s19, s31, s19
	v_add3_u32 v9, v38, v9, s26
	s_waitcnt lgkmcnt(0)
	v_bfe_u32 v10, v40, 16, 1
	v_ashrrev_i32_e32 v43, 31, v42
	v_lshl_add_u64 v[12:13], s[18:19], 0, v[2:3]
	v_lshrrev_b32_e32 v9, 16, v9
	v_add3_u32 v10, v40, v10, s26
	v_lshlrev_b64 v[42:43], 12, v[42:43]
	v_and_or_b32 v9, v10, s27, v9
	v_lshl_add_u64 v[42:43], v[12:13], 0, v[42:43]
	global_store_dwordx4 v[42:43], v[6:9], off
	v_bfe_u32 v10, v41, 16, 1
	v_add3_u32 v10, v41, v10, s26
	v_bfe_u32 v6, v11, 16, 1
	v_add3_u32 v6, v11, v6, s26
	v_bfe_u32 v7, v15, 16, 1
	v_lshrrev_b32_e32 v6, 16, v6
	v_add3_u32 v7, v15, v7, s26
	v_and_or_b32 v6, v7, s27, v6
	v_bfe_u32 v7, v17, 16, 1
	v_add3_u32 v7, v17, v7, s26
	v_bfe_u32 v8, v19, 16, 1
	v_lshrrev_b32_e32 v7, 16, v7
	v_add3_u32 v8, v19, v8, s26
	v_and_or_b32 v7, v8, s27, v7
	v_bfe_u32 v8, v21, 16, 1
	v_add3_u32 v8, v21, v8, s26
	v_bfe_u32 v9, v37, 16, 1
	v_lshrrev_b32_e32 v8, 16, v8
	v_add3_u32 v9, v37, v9, s26
	v_and_or_b32 v8, v9, s27, v8
	v_bfe_u32 v9, v39, 16, 1
	v_add3_u32 v9, v39, v9, s26
	v_lshrrev_b32_e32 v9, 16, v9
	v_and_or_b32 v9, v10, s27, v9
	v_or_b32_e32 v10, s20, v24
	v_ashrrev_i32_e32 v11, 31, v10
	v_lshlrev_b64 v[10:11], 12, v[10:11]
	ds_read2_b32 v[14:15], v23 offset0:16 offset1:24
	v_lshl_add_u64 v[10:11], v[12:13], 0, v[10:11]
	global_store_dwordx4 v[10:11], v[6:9], off
	ds_read2_b32 v[10:11], v23 offset0:49 offset1:57
	ds_read2_b32 v[16:17], v23 offset0:82 offset1:90
	ds_read2_b32 v[18:19], v23 offset0:115 offset1:123
	s_waitcnt lgkmcnt(3)
	v_bfe_u32 v6, v14, 16, 1
	v_add3_u32 v6, v14, v6, s26
	s_waitcnt lgkmcnt(2)
	v_bfe_u32 v7, v10, 16, 1
	ds_read2_b32 v[20:21], v23 offset0:148 offset1:156
	v_lshrrev_b32_e32 v6, 16, v6
	v_add3_u32 v7, v10, v7, s26
	ds_read2_b32 v[36:37], v23 offset0:181 offset1:189
	v_and_or_b32 v6, v7, s27, v6
	s_waitcnt lgkmcnt(3)
	v_bfe_u32 v7, v16, 16, 1
	v_add3_u32 v7, v16, v7, s26
	s_waitcnt lgkmcnt(2)
	v_bfe_u32 v8, v18, 16, 1
	ds_read2_b32 v[38:39], v23 offset0:214 offset1:222
	v_lshrrev_b32_e32 v7, 16, v7
	v_add3_u32 v8, v18, v8, s26
	ds_read2_b32 v[40:41], v23 offset0:247 offset1:255
	v_and_or_b32 v7, v8, s27, v7
	s_waitcnt lgkmcnt(3)
	v_bfe_u32 v8, v20, 16, 1
	v_add3_u32 v8, v20, v8, s26
	s_waitcnt lgkmcnt(2)
	v_bfe_u32 v9, v36, 16, 1
	v_lshrrev_b32_e32 v8, 16, v8
	v_add3_u32 v9, v36, v9, s26
	v_and_or_b32 v8, v9, s27, v8
	s_waitcnt lgkmcnt(1)
	v_bfe_u32 v9, v38, 16, 1
	v_or_b32_e32 v42, s20, v25
	v_add3_u32 v9, v38, v9, s26
	s_waitcnt lgkmcnt(0)
	v_bfe_u32 v10, v40, 16, 1
	v_ashrrev_i32_e32 v43, 31, v42
	v_lshrrev_b32_e32 v9, 16, v9
	v_add3_u32 v10, v40, v10, s26
	v_lshlrev_b64 v[42:43], 12, v[42:43]
	v_and_or_b32 v9, v10, s27, v9
	v_lshl_add_u64 v[42:43], v[12:13], 0, v[42:43]
	global_store_dwordx4 v[42:43], v[6:9], off
	v_bfe_u32 v10, v41, 16, 1
	v_add3_u32 v10, v41, v10, s26
	v_bfe_u32 v6, v15, 16, 1
	v_add3_u32 v6, v15, v6, s26
	v_bfe_u32 v7, v11, 16, 1
	v_lshrrev_b32_e32 v6, 16, v6
	v_add3_u32 v7, v11, v7, s26
	v_and_or_b32 v6, v7, s27, v6
	v_bfe_u32 v7, v17, 16, 1
	v_add3_u32 v7, v17, v7, s26
	v_bfe_u32 v8, v19, 16, 1
	v_lshrrev_b32_e32 v7, 16, v7
	v_add3_u32 v8, v19, v8, s26
	v_and_or_b32 v7, v8, s27, v7
	v_bfe_u32 v8, v21, 16, 1
	v_add3_u32 v8, v21, v8, s26
	v_bfe_u32 v9, v37, 16, 1
	v_lshrrev_b32_e32 v8, 16, v8
	v_add3_u32 v9, v37, v9, s26
	v_and_or_b32 v8, v9, s27, v8
	v_bfe_u32 v9, v39, 16, 1
	v_add3_u32 v9, v39, v9, s26
	v_lshrrev_b32_e32 v9, 16, v9
	v_and_or_b32 v9, v10, s27, v9
	v_or_b32_e32 v10, s20, v26
	v_ashrrev_i32_e32 v11, 31, v10
	v_lshlrev_b64 v[10:11], 12, v[10:11]
	v_lshl_add_u64 v[10:11], v[12:13], 0, v[10:11]
	global_store_dwordx4 v[10:11], v[6:9], off
	s_waitcnt lgkmcnt(0)
	s_branch .LBB0_10
.Lconv_ret:
	s_cmp_eq_u32 s100, 1
	s_cbranch_scc1 .Lslot_a_ret
	s_cmp_eq_u32 s100, 2
	s_cbranch_scc1 .Lslot_w_ret

.LBB0_143:
	v_readlane_b32 s98, v254, 35
	v_readlane_b32 s100, v254, 45
	s_cmpk_lt_u32 s98, 0x80
	s_cbranch_scc1 .Lslot_a_done
	s_cmp_lg_u64 s[10:11], 0
	s_cbranch_scc0 .Lsa_f1
	s_cmp_eq_u32 s100, 0
	s_cbranch_scc0 .Lsa_f0l1
	s_mov_b32 s101, 0x3400
	s_mov_b32 s99, 0x60e0
	s_branch .Lsa_go
.Lsa_f0l1:
	s_mov_b32 s101, 0xcc80
	s_mov_b32 s99, 0xfbc0
	s_branch .Lsa_go
.Lsa_f1:
	s_cmp_eq_u32 s100, 0
	s_cbranch_scc0 .Lsa_f1l1
	s_mov_b32 s101, 0x95d0
	s_mov_b32 s99, 0xcc80
	s_branch .Lsa_go
.Lsa_f1l1:
	s_mov_b32 s101, 0x12b00
	s_mov_b32 s99, 0x14100
.Lsa_go:
	s_sub_i32 s98, s98, 0x80
	s_lshl_b32 s98, s98, 3
	s_add_i32 s101, s101, s98
	s_movk_i32 s98, 0x400
	s_mov_b32 s100, 1
	s_branch .Lconv_entry
.Lslot_a_ret:
	s_movk_i32 s3, 0x1000
	s_mov_b32 s33, 0xa2f9836e

.LBB0_362:
	v_readlane_b32 s98, v254, 35
	v_readlane_b32 s100, v254, 45
	s_cmpk_lt_u32 s98, 0x80
	s_cbranch_scc1 .Lslot_w_done
	s_cmp_eq_u32 s100, 0
	s_cbranch_scc0 .Lsw_f0l1
	s_mov_b32 s101, 0x60e0
	s_mov_b32 s99, 0x95d0
	s_branch .Lsw_go
.Lsw_f0l1:
	s_mov_b32 s101, 0xfbc0
	s_mov_b32 s99, 0x12b00
.Lsw_go:
	s_sub_i32 s98, s98, 0x80
	s_lshl_b32 s98, s98, 3
	s_add_i32 s101, s101, s98
	s_movk_i32 s98, 0x400
	s_mov_b32 s100, 2
	s_branch .Lconv_entry

	.amdhsa_kernel _Z14fwd_megakernel4Args
		.amdhsa_group_segment_fixed_size 0
		.amdhsa_private_segment_fixed_size 0
		.amdhsa_kernarg_size 520
		.amdhsa_user_sgpr_count 2
		.amdhsa_user_sgpr_dispatch_ptr 0
		.amdhsa_user_sgpr_queue_ptr 0
		.amdhsa_user_sgpr_kernarg_segment_ptr 1
		.amdhsa_user_sgpr_dispatch_id 0
		.amdhsa_user_sgpr_kernarg_preload_length 0
		.amdhsa_user_sgpr_kernarg_preload_offset 0
		.amdhsa_user_sgpr_private_segment_size 0
		.amdhsa_uses_dynamic_stack 0
		.amdhsa_enable_private_segment 0
		.amdhsa_system_sgpr_workgroup_id_x 1
		.amdhsa_system_sgpr_workgroup_id_y 0
		.amdhsa_system_sgpr_workgroup_id_z 0
		.amdhsa_system_sgpr_workgroup_info 0
		.amdhsa_system_vgpr_workitem_id 2
		.amdhsa_next_free_vgpr 256
		.amdhsa_next_free_sgpr 102
		.amdhsa_accum_offset 256
		.amdhsa_reserve_vcc 1
		.amdhsa_float_round_mode_32 0
		.amdhsa_float_round_mode_16_64 0
		.amdhsa_float_denorm_mode_32 3
		.amdhsa_float_denorm_mode_16_64 3
		.amdhsa_dx10_clamp 1
		.amdhsa_ieee_mode 1
		.amdhsa_fp16_overflow 0
		.amdhsa_tg_split 0
		.amdhsa_exception_fp_ieee_invalid_op 0
		.amdhsa_exception_fp_denorm_src 0
		.amdhsa_exception_fp_ieee_div_zero 0
		.amdhsa_exception_fp_ieee_overflow 0
		.amdhsa_exception_fp_ieee_underflow 0
		.amdhsa_exception_fp_ieee_inexact 0
		.amdhsa_exception_int_div_zero 0
	.end_amdhsa_kernel

amdhsa.kernels:
  - .agpr_count:     0
    .args:
      - .offset:         0
        .size:           264
        .value_kind:     by_value
      - .offset:         264
        .size:           4
        .value_kind:     hidden_block_count_x
      - .offset:         268
        .size:           4
        .value_kind:     hidden_block_count_y
      - .offset:         272
        .size:           4
        .value_kind:     hidden_block_count_z
      - .offset:         276
        .size:           2
        .value_kind:     hidden_group_size_x
      - .offset:         278
        .size:           2
        .value_kind:     hidden_group_size_y
      - .offset:         280
        .size:           2
        .value_kind:     hidden_group_size_z
      - .offset:         282
        .size:           2
        .value_kind:     hidden_remainder_x
      - .offset:         284
        .size:           2
        .value_kind:     hidden_remainder_y
      - .offset:         286
        .size:           2
        .value_kind:     hidden_remainder_z
      - .offset:         304
        .size:           8
        .value_kind:     hidden_global_offset_x
      - .offset:         312
        .size:           8
        .value_kind:     hidden_global_offset_y
      - .offset:         320
        .size:           8
        .value_kind:     hidden_global_offset_z
      - .offset:         328
        .size:           2
        .value_kind:     hidden_grid_dims
      - .offset:         352
        .size:           8
        .value_kind:     hidden_multigrid_sync_arg
      - .offset:         384
        .size:           4
        .value_kind:     hidden_dynamic_lds_size
    .group_segment_fixed_size: 0
    .kernarg_segment_align: 8
    .kernarg_segment_size: 520
    .language:       OpenCL C
    .language_version:
      - 2
      - 0
    .max_flat_workgroup_size: 512
    .name:           _Z14fwd_megakernel4Args
    .private_segment_fixed_size: 0
    .sgpr_count:     108
    .sgpr_spill_count: 75
    .symbol:         _Z14fwd_megakernel4Args.kd
    .uniform_work_group_size: 1
    .uses_dynamic_stack: false
    .vgpr_count:     256
    .vgpr_spill_count: 0
    .wavefront_size: 64
